# sum-reduction steps (lane^16, lane^32) in the in-proj epilogue use v_permlane16/32_swap instead of ds_bpermute
# baseline (speedup 1.0000x reference)
.LBB0_227:
	s_cmp_lt_i32 s40, 64
	s_cselect_b64 s[38:39], -1, 0
	s_lshl_b32 s29, s40, 8
	s_and_b32 s27, s29, 0x1f00
	s_sub_i32 s8, s40, 64
	s_ashr_i32 s9, s40, 5
	s_addk_i32 s27, 0x100
	s_cmp_gt_i32 s40, 63
	s_cselect_b32 s44, s8, s9
	s_cselect_b32 s27, 0, s27
	v_add_u32_e32 v204, s29, v171
	s_mov_b64 s[40:41], -1
	s_mov_b64 s[8:9], 0
	s_cmp_lt_i32 s13, 1
	s_mov_b64 s[46:47], 0
	s_cbranch_scc1 .LBB0_231
	s_cmp_eq_u32 s13, 1
	s_mov_b64 s[46:47], -1
	s_cbranch_scc0 .LBB0_230
	v_mul_f32_e32 v0, 0x3d372713, v162
	v_mul_f32_e32 v0, v162, v0
	v_fma_f32 v0, v162, v0, v162
	v_mul_f32_e32 v0, 0x3f4c422a, v0
	v_add_f32_e32 v0, v0, v0
	v_mul_f32_e32 v0, 0xbfb8aa3b, v0
	v_exp_f32_e32 v0, v0
	v_mul_f32_e32 v146, 0x3d372713, v163
	v_mul_f32_e32 v146, v163, v146
	v_fma_f32 v146, v163, v146, v163
	v_add_f32_e32 v0, 1.0, v0
	v_rcp_f32_e32 v156, v0
	v_mul_f32_e32 v0, 0x3f4c422a, v146
	v_mul_f32_e32 v146, 0x3d372713, v164
	v_mul_f32_e32 v146, v164, v146
	v_mul_f32_e32 v147, 0x3d372713, v165
	v_fma_f32 v146, v164, v146, v164
	v_mul_f32_e32 v147, v165, v147
	v_add_f32_e32 v0, v0, v0
	v_mul_f32_e32 v146, 0x3f4c422a, v146
	v_fma_f32 v147, v165, v147, v165
	v_mul_f32_e32 v0, 0xbfb8aa3b, v0
	v_add_f32_e32 v146, v146, v146
	v_mul_f32_e32 v147, 0x3f4c422a, v147
	v_exp_f32_e32 v0, v0
	v_mul_f32_e32 v146, 0xbfb8aa3b, v146
	v_add_f32_e32 v147, v147, v147
	v_exp_f32_e32 v146, v146
	v_mul_f32_e32 v147, 0xbfb8aa3b, v147
	v_exp_f32_e32 v147, v147
	v_add_f32_e32 v0, 1.0, v0
	v_rcp_f32_e32 v157, v0
	v_add_f32_e32 v0, 1.0, v146
	v_rcp_f32_e32 v158, v0
	v_add_f32_e32 v0, 1.0, v147
	v_rcp_f32_e32 v159, v0
	v_mul_f32_e32 v0, 0x3d372713, v142
	v_mul_f32_e32 v0, v142, v0
	v_mul_f32_e32 v146, 0x3d372713, v143
	v_fma_f32 v0, v142, v0, v142
	v_mul_f32_e32 v146, v143, v146
	v_mul_f32_e32 v147, 0x3d372713, v144
	v_mul_f32_e32 v0, 0x3f4c422a, v0
	v_fma_f32 v146, v143, v146, v143
	v_mul_f32_e32 v147, v144, v147
	v_add_f32_e32 v0, v0, v0
	v_mul_f32_e32 v146, 0x3f4c422a, v146
	v_fma_f32 v147, v144, v147, v144
	v_mul_f32_e32 v0, 0xbfb8aa3b, v0
	v_add_f32_e32 v146, v146, v146
	v_mul_f32_e32 v147, 0x3f4c422a, v147
	v_exp_f32_e32 v0, v0
	v_mul_f32_e32 v146, 0xbfb8aa3b, v146
	v_add_f32_e32 v147, v147, v147
	v_exp_f32_e32 v146, v146
	v_mul_f32_e32 v147, 0xbfb8aa3b, v147
	v_exp_f32_e32 v147, v147
	v_add_f32_e32 v0, 1.0, v0
	v_rcp_f32_e32 v160, v0
	v_add_f32_e32 v0, 1.0, v146
	v_rcp_f32_e32 v161, v0
	v_add_f32_e32 v0, 1.0, v147
	v_rcp_f32_e32 v205, v0
	v_mul_f32_e32 v0, 0x3d372713, v145
	v_mul_f32_e32 v0, v145, v0
	v_fma_f32 v0, v145, v0, v145
	v_mul_f32_e32 v0, 0x3f4c422a, v0
	v_add_f32_e32 v0, v0, v0
	v_mul_f32_e32 v0, 0xbfb8aa3b, v0
	v_exp_f32_e32 v0, v0
	v_mul_f32_e32 v146, 0x3d372713, v139
	v_mul_f32_e32 v146, v139, v146
	v_fma_f32 v146, v139, v146, v139
	v_add_f32_e32 v0, 1.0, v0
	v_rcp_f32_e32 v206, v0
	v_mul_f32_e32 v0, 0x3d372713, v138
	v_mul_f32_e32 v0, v138, v0
	v_fma_f32 v0, v138, v0, v138
	v_mul_f32_e32 v0, 0x3f4c422a, v0
	v_add_f32_e32 v0, v0, v0
	v_mul_f32_e32 v146, 0x3f4c422a, v146
	v_mul_f32_e32 v0, 0xbfb8aa3b, v0
	v_add_f32_e32 v146, v146, v146
	v_exp_f32_e32 v0, v0
	v_mul_f32_e32 v146, 0xbfb8aa3b, v146
	v_exp_f32_e32 v147, v146
	v_fma_f32 v152, v162, v156, 0
	v_add_f32_e32 v0, 1.0, v0
	v_rcp_f32_e32 v146, v0
	v_add_f32_e32 v0, 1.0, v147
	v_mul_f32_e32 v147, 0x3d372713, v140
	v_mul_f32_e32 v147, v140, v147
	v_fma_f32 v147, v140, v147, v140
	v_mul_f32_e32 v147, 0x3f4c422a, v147
	v_add_f32_e32 v147, v147, v147
	v_mul_f32_e32 v147, 0xbfb8aa3b, v147
	v_exp_f32_e32 v148, v147
	v_mul_f32_e32 v147, 0x3d372713, v141
	v_mul_f32_e32 v147, v141, v147
	v_fma_f32 v147, v141, v147, v141
	v_mul_f32_e32 v147, 0x3f4c422a, v147
	v_fmac_f32_e32 v152, v163, v157
	v_add_f32_e32 v147, v147, v147
	v_fmac_f32_e32 v152, v164, v158
	v_mul_f32_e32 v147, 0xbfb8aa3b, v147
	v_fmac_f32_e32 v152, v165, v159
	v_exp_f32_e32 v149, v147
	v_rcp_f32_e32 v147, v0
	v_fmac_f32_e32 v152, v142, v160
	v_fmac_f32_e32 v152, v143, v161
	v_fmac_f32_e32 v152, v144, v205
	v_add_f32_e32 v0, 1.0, v148
	v_fmac_f32_e32 v152, v145, v206
	v_rcp_f32_e32 v148, v0
	v_add_f32_e32 v0, 1.0, v149
	v_pk_mul_f32 v[150:151], v[138:139], v[146:147]
	v_rcp_f32_e32 v149, v0
	v_add_f32_e32 v0, v152, v150
	v_mul_f32_e32 v152, 0x3d372713, v135
	v_mul_f32_e32 v152, v135, v152
	v_fma_f32 v152, v135, v152, v135
	v_mul_f32_e32 v152, 0x3f4c422a, v152
	v_add_f32_e32 v152, v152, v152
	v_mul_f32_e32 v152, 0xbfb8aa3b, v152
	v_exp_f32_e32 v152, v152
	v_add_f32_e32 v0, v151, v0
	v_pk_mul_f32 v[150:151], v[140:141], v[148:149]
	v_mul_f32_e32 v153, 0x3d372713, v137
	v_add_f32_e32 v0, v150, v0
	v_mul_f32_e32 v150, 0x3d372713, v134
	v_mul_f32_e32 v150, v134, v150
	v_fma_f32 v150, v134, v150, v134
	v_add_f32_e32 v0, v151, v0
	v_add_f32_e32 v151, 1.0, v152
	v_mul_f32_e32 v152, 0x3d372713, v136
	v_mul_f32_e32 v150, 0x3f4c422a, v150
	v_mul_f32_e32 v152, v136, v152
	v_mul_f32_e32 v153, v137, v153
	v_add_f32_e32 v150, v150, v150
	v_fma_f32 v152, v136, v152, v136
	v_fma_f32 v153, v137, v153, v137
	v_mul_f32_e32 v150, 0xbfb8aa3b, v150
	v_mul_f32_e32 v152, 0x3f4c422a, v152
	v_mul_f32_e32 v153, 0x3f4c422a, v153
	v_exp_f32_e32 v150, v150
	v_add_f32_e32 v152, v152, v152
	v_add_f32_e32 v153, v153, v153
	v_mul_f32_e32 v152, 0xbfb8aa3b, v152
	v_mul_f32_e32 v153, 0xbfb8aa3b, v153
	v_exp_f32_e32 v152, v152
	v_exp_f32_e32 v153, v153
	v_add_f32_e32 v150, 1.0, v150
	v_rcp_f32_e32 v150, v150
	v_rcp_f32_e32 v151, v151
	v_add_f32_e32 v152, 1.0, v152
	v_add_f32_e32 v153, 1.0, v153
	v_rcp_f32_e32 v152, v152
	v_rcp_f32_e32 v153, v153
	v_pk_mul_f32 v[154:155], v[134:135], v[150:151]
	s_mov_b64 s[46:47], 0
	v_add_f32_e32 v0, v154, v0
	v_add_f32_e32 v0, v155, v0
	v_pk_mul_f32 v[154:155], v[136:137], v[152:153]
	s_nop 0
	v_add_f32_e32 v0, v154, v0
	v_add_f32_e32 v0, v155, v0
	v_and_b32_e32 v155, 64, v224
	v_xor_b32_e32 v154, 16, v224
	v_add_u32_e32 v155, 64, v155
	v_cmp_lt_i32_e32 vcc, v154, v155
	s_nop 1
	v_cndmask_b32_e32 v154, v224, v154, vcc
	v_lshlrev_b32_e32 v207, 2, v154
	v_mov_b32_e32 v250, v0
	v_mov_b32_e32 v154, v0
	s_nop 1
	v_permlane16_swap_b32_e32 v154, v250
	s_waitcnt lgkmcnt(0)
	v_add_f32_e32 v0, v154, v250
	v_xor_b32_e32 v154, 32, v224
	v_cmp_lt_i32_e32 vcc, v154, v155
	s_nop 1
	v_cndmask_b32_e32 v154, v224, v154, vcc
	v_lshlrev_b32_e32 v214, 2, v154
	v_mov_b32_e32 v250, v0
	v_mov_b32_e32 v154, v0
	s_nop 1
	v_permlane32_swap_b32_e32 v154, v250
	s_waitcnt lgkmcnt(0)
	v_add_f32_e32 v0, v154, v250
	v_mul_f32_e32 v0, 0x3c800000, v0
	v_fma_f32 v216, v163, v157, -v0
	v_fma_f32 v215, v162, v156, -v0
	v_mul_f32_e32 v156, v216, v216
	v_fmac_f32_e32 v156, v215, v215
	v_fma_f32 v158, v164, v158, -v0
	v_fmac_f32_e32 v156, v158, v158
	v_fma_f32 v159, v165, v159, -v0
	v_fmac_f32_e32 v156, v159, v159
	v_fma_f32 v160, v142, v160, -v0
	v_fmac_f32_e32 v156, v160, v160
	v_fma_f32 v161, v143, v161, -v0
	v_fmac_f32_e32 v156, v161, v161
	v_fma_f32 v217, v144, v205, -v0
	v_fmac_f32_e32 v156, v217, v217
	v_fma_f32 v206, v145, v206, -v0
	v_pk_fma_f32 v[154:155], v[138:139], v[146:147], v[0:1] op_sel_hi:[1,1,0] neg_lo:[0,0,1] neg_hi:[0,0,1]
	v_fmac_f32_e32 v156, v206, v206
	v_pk_mul_f32 v[146:147], v[154:155], v[154:155]
	v_pk_fma_f32 v[150:151], v[134:135], v[150:151], v[0:1] op_sel_hi:[1,1,0] neg_lo:[0,0,1] neg_hi:[0,0,1]
	v_add_f32_e32 v146, v146, v156
	v_pk_fma_f32 v[156:157], v[140:141], v[148:149], v[0:1] op_sel_hi:[1,1,0] neg_lo:[0,0,1] neg_hi:[0,0,1]
	v_add_f32_e32 v205, v147, v146
	v_pk_mul_f32 v[146:147], v[156:157], v[156:157]
	v_pk_fma_f32 v[152:153], v[136:137], v[152:153], v[0:1] op_sel_hi:[1,1,0] neg_lo:[0,0,1] neg_hi:[0,0,1]
	v_add_f32_e32 v146, v146, v205
	v_add_f32_e32 v148, v147, v146
	v_pk_mul_f32 v[146:147], v[150:151], v[150:151]
	v_ashrrev_i32_e32 v205, 31, v204
	v_add_f32_e32 v146, v146, v148
	v_add_f32_e32 v148, v147, v146
	v_pk_mul_f32 v[146:147], v[152:153], v[152:153]
	s_nop 0
	v_add_f32_e32 v0, v146, v148
	v_add_f32_e32 v0, v147, v0
	v_mov_b32_e32 v250, v0
	v_mov_b32_e32 v146, v0
	s_nop 1
	v_permlane16_swap_b32_e32 v146, v250
	s_waitcnt lgkmcnt(0)
	v_add_f32_e32 v0, v146, v250
	v_mov_b32_e32 v250, v0
	v_mov_b32_e32 v146, v0
	s_nop 1
	v_permlane32_swap_b32_e32 v146, v250
	s_waitcnt lgkmcnt(0)
	v_add_f32_e32 v0, v146, v250
	v_fmamk_f32 v0, v0, 0x3c800000, v222
	v_mul_f32_e32 v146, 0x4b800000, v0
	v_cmp_gt_f32_e32 vcc, s78, v0
	s_nop 1
	v_cndmask_b32_e32 v0, v0, v146, vcc
	v_rsq_f32_e32 v0, v0
	s_nop 0
	v_mul_f32_e32 v146, 0x45800000, v0
	v_cndmask_b32_e32 v0, v0, v146, vcc
	v_lshlrev_b64 v[146:147], 9, v[204:205]
	v_mul_f32_e32 v148, v215, v0
	v_mul_f32_e32 v149, v216, v0
	v_mul_f32_e32 v205, v158, v0
	v_mul_f32_e32 v207, v159, v0
	v_mul_f32_e32 v160, v160, v0
	v_mul_f32_e32 v161, v161, v0
	v_mul_f32_e32 v214, v217, v0
	v_mul_f32_e32 v206, v206, v0
	v_lshl_add_u64 v[158:159], v[196:197], 0, v[146:147]
	v_cvt_pk_bf16_f32 v146, v148, v149
	v_cvt_pk_bf16_f32 v147, v205, v207
	v_cvt_pk_bf16_f32 v148, v160, v161
	v_cvt_pk_bf16_f32 v149, v214, v206
	global_store_dwordx4 v[158:159], v[146:149], off
	v_mul_f32_e32 v150, v150, v0
	v_mul_f32_e32 v151, v151, v0
	v_mul_f32_e32 v146, v154, v0
	v_mul_f32_e32 v147, v155, v0
	v_mul_f32_e32 v148, v156, v0
	v_mul_f32_e32 v149, v157, v0
	v_mul_f32_e32 v152, v152, v0
	v_mul_f32_e32 v0, v153, v0
	v_cvt_pk_bf16_f32 v146, v146, v147
	v_cvt_pk_bf16_f32 v147, v148, v149
	v_cvt_pk_bf16_f32 v148, v150, v151
	v_cvt_pk_bf16_f32 v149, v152, v0
	global_store_dwordx4 v[158:159], v[146:149], off offset:64

.LBB0_241:
	s_and_b64 vcc, exec, s[0:1]
	s_cbranch_vccz .LBB0_269
	v_mul_f32_e32 v0, v163, v163
	v_fmac_f32_e32 v0, v162, v162
	v_fmac_f32_e32 v0, v164, v164
	v_fmac_f32_e32 v0, v165, v165
	v_fmac_f32_e32 v0, v142, v142
	v_fmac_f32_e32 v0, v143, v143
	v_fmac_f32_e32 v0, v144, v144
	v_fmac_f32_e32 v0, v145, v145
	v_pk_mul_f32 v[148:149], v[138:139], v[138:139]
	v_pk_mul_f32 v[146:147], v[140:141], v[140:141]
	v_add_f32_e32 v0, v0, v148
	v_add_f32_e32 v0, v149, v0
	v_add_f32_e32 v0, v146, v0
	v_add_f32_e32 v0, v147, v0
	v_pk_mul_f32 v[148:149], v[134:135], v[134:135]
	v_pk_mul_f32 v[146:147], v[136:137], v[136:137]
	v_add_f32_e32 v0, v148, v0
	v_add_f32_e32 v0, v149, v0
	v_add_f32_e32 v0, v146, v0
	v_add_f32_e32 v0, v147, v0
	v_and_b32_e32 v147, 64, v224
	v_xor_b32_e32 v146, 16, v224
	v_add_u32_e32 v147, 64, v147
	v_cmp_lt_i32_e32 vcc, v146, v147
	s_nop 1
	v_cndmask_b32_e32 v146, v224, v146, vcc
	v_lshlrev_b32_e32 v146, 2, v146
	v_mov_b32_e32 v250, v0
	v_mov_b32_e32 v146, v0
	s_nop 1
	v_permlane16_swap_b32_e32 v146, v250
	s_waitcnt lgkmcnt(0)
	v_add_f32_e32 v205, v146, v250
	v_xor_b32_e32 v0, 32, v224
	v_cmp_lt_i32_e32 vcc, v0, v147
	s_nop 1
	v_cndmask_b32_e32 v0, v224, v0, vcc
	v_lshlrev_b32_e32 v215, 2, v0
	ds_bpermute_b32 v206, v215, v205
	v_cndmask_b32_e64 v0, 0, 1, s[38:39]
	v_cmp_ne_u32_e64 s[0:1], 1, v0
	s_andn2_b64 vcc, exec, s[38:39]
	s_cbranch_vccnz .LBB0_244
	v_lshlrev_b32_e32 v0, 1, v204
	v_and_b32_e32 v0, 0x3f80, v0
	v_lshl_add_u64 v[158:159], v[186:187], 0, v[0:1]
	global_load_dwordx4 v[146:149], v[158:159], off offset:48
	global_load_dwordx4 v[150:153], v[158:159], off offset:32
	global_load_dwordx4 v[154:157], v[158:159], off offset:16
	s_nop 0
	global_load_dwordx4 v[158:161], v[158:159], off

.LBB0_272:
	v_or_b32_e32 v0, 16, v171
	v_add_u32_e32 v204, s29, v0
	s_mov_b64 s[44:45], -1
	s_mov_b64 s[0:1], 0
	s_cmp_lt_i32 s13, 1
	s_mov_b64 s[8:9], 0
	s_cbranch_scc1 .LBB0_276
	s_cmp_eq_u32 s13, 1
	s_mov_b64 s[8:9], -1
	s_cbranch_scc0 .LBB0_275
	v_mul_f32_e32 v0, 0x3d372713, v130
	v_mul_f32_e32 v0, v130, v0
	v_fma_f32 v0, v130, v0, v130
	v_mul_f32_e32 v0, 0x3f4c422a, v0
	v_add_f32_e32 v0, v0, v0
	v_mul_f32_e32 v0, 0xbfb8aa3b, v0
	v_exp_f32_e32 v0, v0
	v_mul_f32_e32 v134, 0x3d372713, v131
	v_mul_f32_e32 v134, v131, v134
	v_fma_f32 v134, v131, v134, v131
	v_add_f32_e32 v0, 1.0, v0
	v_rcp_f32_e32 v144, v0
	v_mul_f32_e32 v0, 0x3f4c422a, v134
	v_mul_f32_e32 v134, 0x3d372713, v132
	v_mul_f32_e32 v134, v132, v134
	v_mul_f32_e32 v135, 0x3d372713, v133
	v_fma_f32 v134, v132, v134, v132
	v_mul_f32_e32 v135, v133, v135
	v_add_f32_e32 v0, v0, v0
	v_mul_f32_e32 v134, 0x3f4c422a, v134
	v_fma_f32 v135, v133, v135, v133
	v_mul_f32_e32 v0, 0xbfb8aa3b, v0
	v_add_f32_e32 v134, v134, v134
	v_mul_f32_e32 v135, 0x3f4c422a, v135
	v_exp_f32_e32 v0, v0
	v_mul_f32_e32 v134, 0xbfb8aa3b, v134
	v_add_f32_e32 v135, v135, v135
	v_exp_f32_e32 v134, v134
	v_mul_f32_e32 v135, 0xbfb8aa3b, v135
	v_exp_f32_e32 v135, v135
	v_add_f32_e32 v0, 1.0, v0
	v_rcp_f32_e32 v145, v0
	v_add_f32_e32 v0, 1.0, v134
	v_rcp_f32_e32 v162, v0
	v_add_f32_e32 v0, 1.0, v135
	v_rcp_f32_e32 v163, v0
	v_mul_f32_e32 v0, 0x3d372713, v126
	v_mul_f32_e32 v0, v126, v0
	v_mul_f32_e32 v134, 0x3d372713, v127
	v_fma_f32 v0, v126, v0, v126
	v_mul_f32_e32 v134, v127, v134
	v_mul_f32_e32 v135, 0x3d372713, v128
	v_mul_f32_e32 v0, 0x3f4c422a, v0
	v_fma_f32 v134, v127, v134, v127
	v_mul_f32_e32 v135, v128, v135
	v_add_f32_e32 v0, v0, v0
	v_mul_f32_e32 v134, 0x3f4c422a, v134
	v_fma_f32 v135, v128, v135, v128
	v_mul_f32_e32 v0, 0xbfb8aa3b, v0
	v_add_f32_e32 v134, v134, v134
	v_mul_f32_e32 v135, 0x3f4c422a, v135
	v_exp_f32_e32 v0, v0
	v_mul_f32_e32 v134, 0xbfb8aa3b, v134
	v_add_f32_e32 v135, v135, v135
	v_exp_f32_e32 v134, v134
	v_mul_f32_e32 v135, 0xbfb8aa3b, v135
	v_exp_f32_e32 v135, v135
	v_add_f32_e32 v0, 1.0, v0
	v_rcp_f32_e32 v164, v0
	v_add_f32_e32 v0, 1.0, v134
	v_rcp_f32_e32 v165, v0
	v_add_f32_e32 v0, 1.0, v135
	v_rcp_f32_e32 v205, v0
	v_mul_f32_e32 v0, 0x3d372713, v129
	v_mul_f32_e32 v0, v129, v0
	v_fma_f32 v0, v129, v0, v129
	v_mul_f32_e32 v0, 0x3f4c422a, v0
	v_add_f32_e32 v0, v0, v0
	v_mul_f32_e32 v0, 0xbfb8aa3b, v0
	v_exp_f32_e32 v0, v0
	v_mul_f32_e32 v134, 0x3d372713, v123
	v_mul_f32_e32 v134, v123, v134
	v_fma_f32 v134, v123, v134, v123
	v_add_f32_e32 v0, 1.0, v0
	v_rcp_f32_e32 v206, v0
	v_mul_f32_e32 v0, 0x3d372713, v122
	v_mul_f32_e32 v0, v122, v0
	v_fma_f32 v0, v122, v0, v122
	v_mul_f32_e32 v0, 0x3f4c422a, v0
	v_add_f32_e32 v0, v0, v0
	v_mul_f32_e32 v134, 0x3f4c422a, v134
	v_mul_f32_e32 v0, 0xbfb8aa3b, v0
	v_add_f32_e32 v134, v134, v134
	v_exp_f32_e32 v0, v0
	v_mul_f32_e32 v134, 0xbfb8aa3b, v134
	v_exp_f32_e32 v135, v134
	v_fma_f32 v140, v130, v144, 0
	v_add_f32_e32 v0, 1.0, v0
	v_rcp_f32_e32 v134, v0
	v_add_f32_e32 v0, 1.0, v135
	v_mul_f32_e32 v135, 0x3d372713, v124
	v_mul_f32_e32 v135, v124, v135
	v_fma_f32 v135, v124, v135, v124
	v_mul_f32_e32 v135, 0x3f4c422a, v135
	v_add_f32_e32 v135, v135, v135
	v_mul_f32_e32 v135, 0xbfb8aa3b, v135
	v_exp_f32_e32 v136, v135
	v_mul_f32_e32 v135, 0x3d372713, v125
	v_mul_f32_e32 v135, v125, v135
	v_fma_f32 v135, v125, v135, v125
	v_mul_f32_e32 v135, 0x3f4c422a, v135
	v_fmac_f32_e32 v140, v131, v145
	v_add_f32_e32 v135, v135, v135
	v_fmac_f32_e32 v140, v132, v162
	v_mul_f32_e32 v135, 0xbfb8aa3b, v135
	v_fmac_f32_e32 v140, v133, v163
	v_exp_f32_e32 v137, v135
	v_rcp_f32_e32 v135, v0
	v_fmac_f32_e32 v140, v126, v164
	v_fmac_f32_e32 v140, v127, v165
	v_fmac_f32_e32 v140, v128, v205
	v_add_f32_e32 v0, 1.0, v136
	v_fmac_f32_e32 v140, v129, v206
	v_rcp_f32_e32 v136, v0
	v_add_f32_e32 v0, 1.0, v137
	v_pk_mul_f32 v[138:139], v[122:123], v[134:135]
	v_rcp_f32_e32 v137, v0
	v_add_f32_e32 v0, v140, v138
	v_mul_f32_e32 v140, 0x3d372713, v119
	v_mul_f32_e32 v140, v119, v140
	v_fma_f32 v140, v119, v140, v119
	v_mul_f32_e32 v140, 0x3f4c422a, v140
	v_add_f32_e32 v140, v140, v140
	v_mul_f32_e32 v140, 0xbfb8aa3b, v140
	v_exp_f32_e32 v140, v140
	v_add_f32_e32 v0, v139, v0
	v_pk_mul_f32 v[138:139], v[124:125], v[136:137]
	v_mul_f32_e32 v141, 0x3d372713, v121
	v_add_f32_e32 v0, v138, v0
	v_mul_f32_e32 v138, 0x3d372713, v118
	v_mul_f32_e32 v138, v118, v138
	v_fma_f32 v138, v118, v138, v118
	v_add_f32_e32 v0, v139, v0
	v_add_f32_e32 v139, 1.0, v140
	v_mul_f32_e32 v140, 0x3d372713, v120
	v_mul_f32_e32 v138, 0x3f4c422a, v138
	v_mul_f32_e32 v140, v120, v140
	v_mul_f32_e32 v141, v121, v141
	v_add_f32_e32 v138, v138, v138
	v_fma_f32 v140, v120, v140, v120
	v_fma_f32 v141, v121, v141, v121
	v_mul_f32_e32 v138, 0xbfb8aa3b, v138
	v_mul_f32_e32 v140, 0x3f4c422a, v140
	v_mul_f32_e32 v141, 0x3f4c422a, v141
	v_exp_f32_e32 v138, v138
	v_add_f32_e32 v140, v140, v140
	v_add_f32_e32 v141, v141, v141
	v_mul_f32_e32 v140, 0xbfb8aa3b, v140
	v_mul_f32_e32 v141, 0xbfb8aa3b, v141
	v_exp_f32_e32 v140, v140
	v_exp_f32_e32 v141, v141
	v_add_f32_e32 v138, 1.0, v138
	v_rcp_f32_e32 v138, v138
	v_rcp_f32_e32 v139, v139
	v_add_f32_e32 v140, 1.0, v140
	v_add_f32_e32 v141, 1.0, v141
	v_rcp_f32_e32 v140, v140
	v_rcp_f32_e32 v141, v141
	v_pk_mul_f32 v[142:143], v[118:119], v[138:139]
	s_mov_b64 s[8:9], 0
	v_add_f32_e32 v0, v142, v0
	v_add_f32_e32 v0, v143, v0
	v_pk_mul_f32 v[142:143], v[120:121], v[140:141]
	s_nop 0
	v_add_f32_e32 v0, v142, v0
	v_add_f32_e32 v0, v143, v0
	v_and_b32_e32 v143, 64, v224
	v_xor_b32_e32 v142, 16, v224
	v_add_u32_e32 v143, 64, v143
	v_cmp_lt_i32_e32 vcc, v142, v143
	s_nop 1
	v_cndmask_b32_e32 v142, v224, v142, vcc
	v_lshlrev_b32_e32 v207, 2, v142
	v_mov_b32_e32 v250, v0
	v_mov_b32_e32 v142, v0
	s_nop 1
	v_permlane16_swap_b32_e32 v142, v250
	s_waitcnt lgkmcnt(0)
	v_add_f32_e32 v0, v142, v250
	v_xor_b32_e32 v142, 32, v224
	v_cmp_lt_i32_e32 vcc, v142, v143
	s_nop 1
	v_cndmask_b32_e32 v142, v224, v142, vcc
	v_lshlrev_b32_e32 v215, 2, v142
	v_mov_b32_e32 v250, v0
	v_mov_b32_e32 v142, v0
	s_nop 1
	v_permlane32_swap_b32_e32 v142, v250
	s_waitcnt lgkmcnt(0)
	v_add_f32_e32 v0, v142, v250
	v_mul_f32_e32 v0, 0x3c800000, v0
	v_fma_f32 v217, v131, v145, -v0
	v_fma_f32 v216, v130, v144, -v0
	v_mul_f32_e32 v144, v217, v217
	v_fmac_f32_e32 v144, v216, v216
	v_fma_f32 v162, v132, v162, -v0
	v_fmac_f32_e32 v144, v162, v162
	v_fma_f32 v163, v133, v163, -v0
	v_fmac_f32_e32 v144, v163, v163
	v_fma_f32 v164, v126, v164, -v0
	v_fmac_f32_e32 v144, v164, v164
	v_fma_f32 v165, v127, v165, -v0
	v_fmac_f32_e32 v144, v165, v165
	v_fma_f32 v218, v128, v205, -v0
	v_fmac_f32_e32 v144, v218, v218
	v_fma_f32 v206, v129, v206, -v0
	v_pk_fma_f32 v[142:143], v[122:123], v[134:135], v[0:1] op_sel_hi:[1,1,0] neg_lo:[0,0,1] neg_hi:[0,0,1]
	v_fmac_f32_e32 v144, v206, v206
	v_pk_mul_f32 v[134:135], v[142:143], v[142:143]
	v_pk_fma_f32 v[138:139], v[118:119], v[138:139], v[0:1] op_sel_hi:[1,1,0] neg_lo:[0,0,1] neg_hi:[0,0,1]
	v_add_f32_e32 v134, v134, v144
	v_pk_fma_f32 v[144:145], v[124:125], v[136:137], v[0:1] op_sel_hi:[1,1,0] neg_lo:[0,0,1] neg_hi:[0,0,1]
	v_add_f32_e32 v205, v135, v134
	v_pk_mul_f32 v[134:135], v[144:145], v[144:145]
	v_pk_fma_f32 v[140:141], v[120:121], v[140:141], v[0:1] op_sel_hi:[1,1,0] neg_lo:[0,0,1] neg_hi:[0,0,1]
	v_add_f32_e32 v134, v134, v205
	v_add_f32_e32 v136, v135, v134
	v_pk_mul_f32 v[134:135], v[138:139], v[138:139]
	v_ashrrev_i32_e32 v205, 31, v204
	v_add_f32_e32 v134, v134, v136
	v_add_f32_e32 v136, v135, v134
	v_pk_mul_f32 v[134:135], v[140:141], v[140:141]
	s_nop 0
	v_add_f32_e32 v0, v134, v136
	v_add_f32_e32 v0, v135, v0
	v_mov_b32_e32 v250, v0
	v_mov_b32_e32 v134, v0
	s_nop 1
	v_permlane16_swap_b32_e32 v134, v250
	s_waitcnt lgkmcnt(0)
	v_add_f32_e32 v0, v134, v250
	v_mov_b32_e32 v250, v0
	v_mov_b32_e32 v134, v0
	s_nop 1
	v_permlane32_swap_b32_e32 v134, v250
	s_waitcnt lgkmcnt(0)
	v_add_f32_e32 v0, v134, v250
	v_fmamk_f32 v0, v0, 0x3c800000, v222
	v_mul_f32_e32 v134, 0x4b800000, v0
	v_cmp_gt_f32_e32 vcc, s14, v0
	s_nop 1
	v_cndmask_b32_e32 v0, v0, v134, vcc
	v_rsq_f32_e32 v0, v0
	s_nop 0
	v_mul_f32_e32 v134, 0x45800000, v0
	v_cndmask_b32_e32 v0, v0, v134, vcc
	v_lshlrev_b64 v[134:135], 9, v[204:205]
	v_mul_f32_e32 v136, v216, v0
	v_mul_f32_e32 v137, v217, v0
	v_mul_f32_e32 v205, v162, v0
	v_mul_f32_e32 v207, v163, v0
	v_mul_f32_e32 v164, v164, v0
	v_mul_f32_e32 v165, v165, v0
	v_mul_f32_e32 v215, v218, v0
	v_mul_f32_e32 v206, v206, v0
	v_lshl_add_u64 v[162:163], v[196:197], 0, v[134:135]
	v_cvt_pk_bf16_f32 v134, v136, v137
	v_cvt_pk_bf16_f32 v135, v205, v207
	v_cvt_pk_bf16_f32 v136, v164, v165
	v_cvt_pk_bf16_f32 v137, v215, v206
	global_store_dwordx4 v[162:163], v[134:137], off
	v_mul_f32_e32 v138, v138, v0
	v_mul_f32_e32 v139, v139, v0
	v_mul_f32_e32 v134, v142, v0
	v_mul_f32_e32 v135, v143, v0
	v_mul_f32_e32 v136, v144, v0
	v_mul_f32_e32 v137, v145, v0
	v_mul_f32_e32 v140, v140, v0
	v_mul_f32_e32 v0, v141, v0
	v_cvt_pk_bf16_f32 v134, v134, v135
	v_cvt_pk_bf16_f32 v135, v136, v137
	v_cvt_pk_bf16_f32 v136, v138, v139
	v_cvt_pk_bf16_f32 v137, v140, v0
	global_store_dwordx4 v[162:163], v[134:137], off offset:64

.LBB0_317:
	v_add_u32_e32 v146, s29, v175
	s_mov_b64 s[44:45], -1
	s_mov_b64 s[0:1], 0
	s_cmp_lt_i32 s13, 1
	s_mov_b64 s[8:9], 0
	s_cbranch_scc1 .LBB0_321
	s_cmp_eq_u32 s13, 1
	s_mov_b64 s[8:9], -1
	s_cbranch_scc0 .LBB0_320
	v_mul_f32_e32 v0, 0x3d372713, v114
	v_mul_f32_e32 v0, v114, v0
	v_fma_f32 v0, v114, v0, v114
	v_mul_f32_e32 v0, 0x3f4c422a, v0
	v_add_f32_e32 v0, v0, v0
	v_mul_f32_e32 v0, 0xbfb8aa3b, v0
	v_exp_f32_e32 v0, v0
	v_mul_f32_e32 v118, 0x3d372713, v115
	v_mul_f32_e32 v118, v115, v118
	v_fma_f32 v118, v115, v118, v115
	v_add_f32_e32 v0, 1.0, v0
	v_rcp_f32_e32 v128, v0
	v_mul_f32_e32 v0, 0x3f4c422a, v118
	v_mul_f32_e32 v118, 0x3d372713, v116
	v_mul_f32_e32 v118, v116, v118
	v_mul_f32_e32 v119, 0x3d372713, v117
	v_fma_f32 v118, v116, v118, v116
	v_mul_f32_e32 v119, v117, v119
	v_add_f32_e32 v0, v0, v0
	v_mul_f32_e32 v118, 0x3f4c422a, v118
	v_fma_f32 v119, v117, v119, v117
	v_mul_f32_e32 v0, 0xbfb8aa3b, v0
	v_add_f32_e32 v118, v118, v118
	v_mul_f32_e32 v119, 0x3f4c422a, v119
	v_exp_f32_e32 v0, v0
	v_mul_f32_e32 v118, 0xbfb8aa3b, v118
	v_add_f32_e32 v119, v119, v119
	v_exp_f32_e32 v118, v118
	v_mul_f32_e32 v119, 0xbfb8aa3b, v119
	v_exp_f32_e32 v119, v119
	v_add_f32_e32 v0, 1.0, v0
	v_rcp_f32_e32 v129, v0
	v_add_f32_e32 v0, 1.0, v118
	v_rcp_f32_e32 v130, v0
	v_add_f32_e32 v0, 1.0, v119
	v_rcp_f32_e32 v131, v0
	v_mul_f32_e32 v0, 0x3d372713, v110
	v_mul_f32_e32 v0, v110, v0
	v_mul_f32_e32 v118, 0x3d372713, v111
	v_fma_f32 v0, v110, v0, v110
	v_mul_f32_e32 v118, v111, v118
	v_mul_f32_e32 v119, 0x3d372713, v112
	v_mul_f32_e32 v0, 0x3f4c422a, v0
	v_fma_f32 v118, v111, v118, v111
	v_mul_f32_e32 v119, v112, v119
	v_add_f32_e32 v0, v0, v0
	v_mul_f32_e32 v118, 0x3f4c422a, v118
	v_fma_f32 v119, v112, v119, v112
	v_mul_f32_e32 v0, 0xbfb8aa3b, v0
	v_add_f32_e32 v118, v118, v118
	v_mul_f32_e32 v119, 0x3f4c422a, v119
	v_exp_f32_e32 v0, v0
	v_mul_f32_e32 v118, 0xbfb8aa3b, v118
	v_add_f32_e32 v119, v119, v119
	v_exp_f32_e32 v118, v118
	v_mul_f32_e32 v119, 0xbfb8aa3b, v119
	v_exp_f32_e32 v119, v119
	v_add_f32_e32 v0, 1.0, v0
	v_rcp_f32_e32 v132, v0
	v_add_f32_e32 v0, 1.0, v118
	v_rcp_f32_e32 v133, v0
	v_add_f32_e32 v0, 1.0, v119
	v_rcp_f32_e32 v147, v0
	v_mul_f32_e32 v0, 0x3d372713, v113
	v_mul_f32_e32 v0, v113, v0
	v_fma_f32 v0, v113, v0, v113
	v_mul_f32_e32 v0, 0x3f4c422a, v0
	v_add_f32_e32 v0, v0, v0
	v_mul_f32_e32 v0, 0xbfb8aa3b, v0
	v_exp_f32_e32 v0, v0
	v_mul_f32_e32 v118, 0x3d372713, v107
	v_mul_f32_e32 v118, v107, v118
	v_fma_f32 v118, v107, v118, v107
	v_add_f32_e32 v0, 1.0, v0
	v_rcp_f32_e32 v148, v0
	v_mul_f32_e32 v0, 0x3d372713, v106
	v_mul_f32_e32 v0, v106, v0
	v_fma_f32 v0, v106, v0, v106
	v_mul_f32_e32 v0, 0x3f4c422a, v0
	v_add_f32_e32 v0, v0, v0
	v_mul_f32_e32 v118, 0x3f4c422a, v118
	v_mul_f32_e32 v0, 0xbfb8aa3b, v0
	v_add_f32_e32 v118, v118, v118
	v_exp_f32_e32 v0, v0
	v_mul_f32_e32 v118, 0xbfb8aa3b, v118
	v_exp_f32_e32 v119, v118
	v_fma_f32 v124, v114, v128, 0
	v_add_f32_e32 v0, 1.0, v0
	v_rcp_f32_e32 v118, v0
	v_add_f32_e32 v0, 1.0, v119
	v_mul_f32_e32 v119, 0x3d372713, v108
	v_mul_f32_e32 v119, v108, v119
	v_fma_f32 v119, v108, v119, v108
	v_mul_f32_e32 v119, 0x3f4c422a, v119
	v_add_f32_e32 v119, v119, v119
	v_mul_f32_e32 v119, 0xbfb8aa3b, v119
	v_exp_f32_e32 v120, v119
	v_mul_f32_e32 v119, 0x3d372713, v109
	v_mul_f32_e32 v119, v109, v119
	v_fma_f32 v119, v109, v119, v109
	v_mul_f32_e32 v119, 0x3f4c422a, v119
	v_fmac_f32_e32 v124, v115, v129
	v_add_f32_e32 v119, v119, v119
	v_fmac_f32_e32 v124, v116, v130
	v_mul_f32_e32 v119, 0xbfb8aa3b, v119
	v_fmac_f32_e32 v124, v117, v131
	v_exp_f32_e32 v121, v119
	v_rcp_f32_e32 v119, v0
	v_fmac_f32_e32 v124, v110, v132
	v_fmac_f32_e32 v124, v111, v133
	v_fmac_f32_e32 v124, v112, v147
	v_add_f32_e32 v0, 1.0, v120
	v_fmac_f32_e32 v124, v113, v148
	v_rcp_f32_e32 v120, v0
	v_add_f32_e32 v0, 1.0, v121
	v_pk_mul_f32 v[122:123], v[106:107], v[118:119]
	v_rcp_f32_e32 v121, v0
	v_add_f32_e32 v0, v124, v122
	v_mul_f32_e32 v124, 0x3d372713, v103
	v_mul_f32_e32 v124, v103, v124
	v_fma_f32 v124, v103, v124, v103
	v_mul_f32_e32 v124, 0x3f4c422a, v124
	v_add_f32_e32 v124, v124, v124
	v_mul_f32_e32 v124, 0xbfb8aa3b, v124
	v_exp_f32_e32 v124, v124
	v_add_f32_e32 v0, v123, v0
	v_pk_mul_f32 v[122:123], v[108:109], v[120:121]
	v_mul_f32_e32 v125, 0x3d372713, v105
	v_add_f32_e32 v0, v122, v0
	v_mul_f32_e32 v122, 0x3d372713, v102
	v_mul_f32_e32 v122, v102, v122
	v_fma_f32 v122, v102, v122, v102
	v_add_f32_e32 v0, v123, v0
	v_add_f32_e32 v123, 1.0, v124
	v_mul_f32_e32 v124, 0x3d372713, v104
	v_mul_f32_e32 v122, 0x3f4c422a, v122
	v_mul_f32_e32 v124, v104, v124
	v_mul_f32_e32 v125, v105, v125
	v_add_f32_e32 v122, v122, v122
	v_fma_f32 v124, v104, v124, v104
	v_fma_f32 v125, v105, v125, v105
	v_mul_f32_e32 v122, 0xbfb8aa3b, v122
	v_mul_f32_e32 v124, 0x3f4c422a, v124
	v_mul_f32_e32 v125, 0x3f4c422a, v125
	v_exp_f32_e32 v122, v122
	v_add_f32_e32 v124, v124, v124
	v_add_f32_e32 v125, v125, v125
	v_mul_f32_e32 v124, 0xbfb8aa3b, v124
	v_mul_f32_e32 v125, 0xbfb8aa3b, v125
	v_exp_f32_e32 v124, v124
	v_exp_f32_e32 v125, v125
	v_add_f32_e32 v122, 1.0, v122
	v_rcp_f32_e32 v122, v122
	v_rcp_f32_e32 v123, v123
	v_add_f32_e32 v124, 1.0, v124
	v_add_f32_e32 v125, 1.0, v125
	v_rcp_f32_e32 v124, v124
	v_rcp_f32_e32 v125, v125
	v_pk_mul_f32 v[126:127], v[102:103], v[122:123]
	s_mov_b64 s[8:9], 0
	v_add_f32_e32 v0, v126, v0
	v_add_f32_e32 v0, v127, v0
	v_pk_mul_f32 v[126:127], v[104:105], v[124:125]
	s_nop 0
	v_add_f32_e32 v0, v126, v0
	v_add_f32_e32 v0, v127, v0
	v_and_b32_e32 v127, 64, v224
	v_xor_b32_e32 v126, 16, v224
	v_add_u32_e32 v127, 64, v127
	v_cmp_lt_i32_e32 vcc, v126, v127
	s_nop 1
	v_cndmask_b32_e32 v126, v224, v126, vcc
	v_lshlrev_b32_e32 v149, 2, v126
	v_mov_b32_e32 v250, v0
	v_mov_b32_e32 v126, v0
	s_nop 1
	v_permlane16_swap_b32_e32 v126, v250
	s_waitcnt lgkmcnt(0)
	v_add_f32_e32 v0, v126, v250
	v_xor_b32_e32 v126, 32, v224
	v_cmp_lt_i32_e32 vcc, v126, v127
	s_nop 1
	v_cndmask_b32_e32 v126, v224, v126, vcc
	v_lshlrev_b32_e32 v150, 2, v126
	v_mov_b32_e32 v250, v0
	v_mov_b32_e32 v126, v0
	s_nop 1
	v_permlane32_swap_b32_e32 v126, v250
	s_waitcnt lgkmcnt(0)
	v_add_f32_e32 v0, v126, v250
	v_mul_f32_e32 v0, 0x3c800000, v0
	v_fma_f32 v152, v115, v129, -v0
	v_fma_f32 v151, v114, v128, -v0
	v_mul_f32_e32 v128, v152, v152
	v_fmac_f32_e32 v128, v151, v151
	v_fma_f32 v130, v116, v130, -v0
	v_fmac_f32_e32 v128, v130, v130
	v_fma_f32 v131, v117, v131, -v0
	v_fmac_f32_e32 v128, v131, v131
	v_fma_f32 v132, v110, v132, -v0
	v_fmac_f32_e32 v128, v132, v132
	v_fma_f32 v133, v111, v133, -v0
	v_fmac_f32_e32 v128, v133, v133
	v_fma_f32 v153, v112, v147, -v0
	v_fmac_f32_e32 v128, v153, v153
	v_fma_f32 v148, v113, v148, -v0
	v_pk_fma_f32 v[126:127], v[106:107], v[118:119], v[0:1] op_sel_hi:[1,1,0] neg_lo:[0,0,1] neg_hi:[0,0,1]
	v_fmac_f32_e32 v128, v148, v148
	v_pk_mul_f32 v[118:119], v[126:127], v[126:127]
	v_pk_fma_f32 v[122:123], v[102:103], v[122:123], v[0:1] op_sel_hi:[1,1,0] neg_lo:[0,0,1] neg_hi:[0,0,1]
	v_add_f32_e32 v118, v118, v128
	v_pk_fma_f32 v[128:129], v[108:109], v[120:121], v[0:1] op_sel_hi:[1,1,0] neg_lo:[0,0,1] neg_hi:[0,0,1]
	v_add_f32_e32 v147, v119, v118
	v_pk_mul_f32 v[118:119], v[128:129], v[128:129]
	v_pk_fma_f32 v[124:125], v[104:105], v[124:125], v[0:1] op_sel_hi:[1,1,0] neg_lo:[0,0,1] neg_hi:[0,0,1]
	v_add_f32_e32 v118, v118, v147
	v_add_f32_e32 v120, v119, v118
	v_pk_mul_f32 v[118:119], v[122:123], v[122:123]
	v_ashrrev_i32_e32 v147, 31, v146
	v_add_f32_e32 v118, v118, v120
	v_add_f32_e32 v120, v119, v118
	v_pk_mul_f32 v[118:119], v[124:125], v[124:125]
	s_nop 0
	v_add_f32_e32 v0, v118, v120
	v_add_f32_e32 v0, v119, v0
	v_mov_b32_e32 v250, v0
	v_mov_b32_e32 v118, v0
	s_nop 1
	v_permlane16_swap_b32_e32 v118, v250
	s_waitcnt lgkmcnt(0)
	v_add_f32_e32 v0, v118, v250
	v_mov_b32_e32 v250, v0
	v_mov_b32_e32 v118, v0
	s_nop 1
	v_permlane32_swap_b32_e32 v118, v250
	s_waitcnt lgkmcnt(0)
	v_add_f32_e32 v0, v118, v250
	v_fmamk_f32 v0, v0, 0x3c800000, v222
	v_mul_f32_e32 v118, 0x4b800000, v0
	v_cmp_gt_f32_e32 vcc, s14, v0
	s_nop 1
	v_cndmask_b32_e32 v0, v0, v118, vcc
	v_rsq_f32_e32 v0, v0
	s_nop 0
	v_mul_f32_e32 v118, 0x45800000, v0
	v_cndmask_b32_e32 v0, v0, v118, vcc
	v_lshlrev_b64 v[118:119], 9, v[146:147]
	v_mul_f32_e32 v120, v151, v0
	v_mul_f32_e32 v121, v152, v0
	v_mul_f32_e32 v147, v130, v0
	v_mul_f32_e32 v149, v131, v0
	v_mul_f32_e32 v132, v132, v0
	v_mul_f32_e32 v133, v133, v0
	v_mul_f32_e32 v150, v153, v0
	v_mul_f32_e32 v148, v148, v0
	v_lshl_add_u64 v[130:131], v[196:197], 0, v[118:119]
	v_cvt_pk_bf16_f32 v118, v120, v121
	v_cvt_pk_bf16_f32 v119, v147, v149
	v_cvt_pk_bf16_f32 v120, v132, v133
	v_cvt_pk_bf16_f32 v121, v150, v148
	global_store_dwordx4 v[130:131], v[118:121], off
	v_mul_f32_e32 v122, v122, v0
	v_mul_f32_e32 v123, v123, v0
	v_mul_f32_e32 v118, v126, v0
	v_mul_f32_e32 v119, v127, v0
	v_mul_f32_e32 v120, v128, v0
	v_mul_f32_e32 v121, v129, v0
	v_mul_f32_e32 v124, v124, v0
	v_mul_f32_e32 v0, v125, v0
	v_cvt_pk_bf16_f32 v118, v118, v119
	v_cvt_pk_bf16_f32 v119, v120, v121
	v_cvt_pk_bf16_f32 v120, v122, v123
	v_cvt_pk_bf16_f32 v121, v124, v0
	global_store_dwordx4 v[130:131], v[118:121], off offset:64

.LBB0_362:
	v_add_u32_e32 v134, s29, v177
	s_mov_b64 s[44:45], -1
	s_mov_b64 s[0:1], 0
	s_cmp_lt_i32 s13, 1
	s_mov_b64 s[8:9], 0
	s_cbranch_scc1 .LBB0_366
	s_cmp_eq_u32 s13, 1
	s_mov_b64 s[8:9], -1
	s_cbranch_scc0 .LBB0_365
	v_mul_f32_e32 v0, 0x3d372713, v98
	v_mul_f32_e32 v0, v98, v0
	v_fma_f32 v0, v98, v0, v98
	v_mul_f32_e32 v0, 0x3f4c422a, v0
	v_add_f32_e32 v0, v0, v0
	v_mul_f32_e32 v0, 0xbfb8aa3b, v0
	v_exp_f32_e32 v0, v0
	v_mul_f32_e32 v102, 0x3d372713, v99
	v_mul_f32_e32 v102, v99, v102
	v_fma_f32 v102, v99, v102, v99
	v_add_f32_e32 v0, 1.0, v0
	v_rcp_f32_e32 v112, v0
	v_mul_f32_e32 v0, 0x3f4c422a, v102
	v_mul_f32_e32 v102, 0x3d372713, v100
	v_mul_f32_e32 v102, v100, v102
	v_mul_f32_e32 v103, 0x3d372713, v101
	v_fma_f32 v102, v100, v102, v100
	v_mul_f32_e32 v103, v101, v103
	v_add_f32_e32 v0, v0, v0
	v_mul_f32_e32 v102, 0x3f4c422a, v102
	v_fma_f32 v103, v101, v103, v101
	v_mul_f32_e32 v0, 0xbfb8aa3b, v0
	v_add_f32_e32 v102, v102, v102
	v_mul_f32_e32 v103, 0x3f4c422a, v103
	v_exp_f32_e32 v0, v0
	v_mul_f32_e32 v102, 0xbfb8aa3b, v102
	v_add_f32_e32 v103, v103, v103
	v_exp_f32_e32 v102, v102
	v_mul_f32_e32 v103, 0xbfb8aa3b, v103
	v_exp_f32_e32 v103, v103
	v_add_f32_e32 v0, 1.0, v0
	v_rcp_f32_e32 v113, v0
	v_add_f32_e32 v0, 1.0, v102
	v_rcp_f32_e32 v114, v0
	v_add_f32_e32 v0, 1.0, v103
	v_rcp_f32_e32 v115, v0
	v_mul_f32_e32 v0, 0x3d372713, v94
	v_mul_f32_e32 v0, v94, v0
	v_mul_f32_e32 v102, 0x3d372713, v95
	v_fma_f32 v0, v94, v0, v94
	v_mul_f32_e32 v102, v95, v102
	v_mul_f32_e32 v103, 0x3d372713, v96
	v_mul_f32_e32 v0, 0x3f4c422a, v0
	v_fma_f32 v102, v95, v102, v95
	v_mul_f32_e32 v103, v96, v103
	v_add_f32_e32 v0, v0, v0
	v_mul_f32_e32 v102, 0x3f4c422a, v102
	v_fma_f32 v103, v96, v103, v96
	v_mul_f32_e32 v0, 0xbfb8aa3b, v0
	v_add_f32_e32 v102, v102, v102
	v_mul_f32_e32 v103, 0x3f4c422a, v103
	v_exp_f32_e32 v0, v0
	v_mul_f32_e32 v102, 0xbfb8aa3b, v102
	v_add_f32_e32 v103, v103, v103
	v_exp_f32_e32 v102, v102
	v_mul_f32_e32 v103, 0xbfb8aa3b, v103
	v_exp_f32_e32 v103, v103
	v_add_f32_e32 v0, 1.0, v0
	v_rcp_f32_e32 v116, v0
	v_add_f32_e32 v0, 1.0, v102
	v_rcp_f32_e32 v117, v0
	v_add_f32_e32 v0, 1.0, v103
	v_rcp_f32_e32 v135, v0
	v_mul_f32_e32 v0, 0x3d372713, v97
	v_mul_f32_e32 v0, v97, v0
	v_fma_f32 v0, v97, v0, v97
	v_mul_f32_e32 v0, 0x3f4c422a, v0
	v_add_f32_e32 v0, v0, v0
	v_mul_f32_e32 v0, 0xbfb8aa3b, v0
	v_exp_f32_e32 v0, v0
	v_mul_f32_e32 v102, 0x3d372713, v91
	v_mul_f32_e32 v102, v91, v102
	v_fma_f32 v102, v91, v102, v91
	v_add_f32_e32 v0, 1.0, v0
	v_rcp_f32_e32 v136, v0
	v_mul_f32_e32 v0, 0x3d372713, v90
	v_mul_f32_e32 v0, v90, v0
	v_fma_f32 v0, v90, v0, v90
	v_mul_f32_e32 v0, 0x3f4c422a, v0
	v_add_f32_e32 v0, v0, v0
	v_mul_f32_e32 v102, 0x3f4c422a, v102
	v_mul_f32_e32 v0, 0xbfb8aa3b, v0
	v_add_f32_e32 v102, v102, v102
	v_exp_f32_e32 v0, v0
	v_mul_f32_e32 v102, 0xbfb8aa3b, v102
	v_exp_f32_e32 v103, v102
	v_fma_f32 v108, v98, v112, 0
	v_add_f32_e32 v0, 1.0, v0
	v_rcp_f32_e32 v102, v0
	v_add_f32_e32 v0, 1.0, v103
	v_mul_f32_e32 v103, 0x3d372713, v92
	v_mul_f32_e32 v103, v92, v103
	v_fma_f32 v103, v92, v103, v92
	v_mul_f32_e32 v103, 0x3f4c422a, v103
	v_add_f32_e32 v103, v103, v103
	v_mul_f32_e32 v103, 0xbfb8aa3b, v103
	v_exp_f32_e32 v104, v103
	v_mul_f32_e32 v103, 0x3d372713, v93
	v_mul_f32_e32 v103, v93, v103
	v_fma_f32 v103, v93, v103, v93
	v_mul_f32_e32 v103, 0x3f4c422a, v103
	v_fmac_f32_e32 v108, v99, v113
	v_add_f32_e32 v103, v103, v103
	v_fmac_f32_e32 v108, v100, v114
	v_mul_f32_e32 v103, 0xbfb8aa3b, v103
	v_fmac_f32_e32 v108, v101, v115
	v_exp_f32_e32 v105, v103
	v_rcp_f32_e32 v103, v0
	v_fmac_f32_e32 v108, v94, v116
	v_fmac_f32_e32 v108, v95, v117
	v_fmac_f32_e32 v108, v96, v135
	v_add_f32_e32 v0, 1.0, v104
	v_fmac_f32_e32 v108, v97, v136
	v_rcp_f32_e32 v104, v0
	v_add_f32_e32 v0, 1.0, v105
	v_pk_mul_f32 v[106:107], v[90:91], v[102:103]
	v_rcp_f32_e32 v105, v0
	v_add_f32_e32 v0, v108, v106
	v_mul_f32_e32 v108, 0x3d372713, v87
	v_mul_f32_e32 v108, v87, v108
	v_fma_f32 v108, v87, v108, v87
	v_mul_f32_e32 v108, 0x3f4c422a, v108
	v_add_f32_e32 v108, v108, v108
	v_mul_f32_e32 v108, 0xbfb8aa3b, v108
	v_exp_f32_e32 v108, v108
	v_add_f32_e32 v0, v107, v0
	v_pk_mul_f32 v[106:107], v[92:93], v[104:105]
	v_mul_f32_e32 v109, 0x3d372713, v89
	v_add_f32_e32 v0, v106, v0
	v_mul_f32_e32 v106, 0x3d372713, v86
	v_mul_f32_e32 v106, v86, v106
	v_fma_f32 v106, v86, v106, v86
	v_add_f32_e32 v0, v107, v0
	v_add_f32_e32 v107, 1.0, v108
	v_mul_f32_e32 v108, 0x3d372713, v88
	v_mul_f32_e32 v106, 0x3f4c422a, v106
	v_mul_f32_e32 v108, v88, v108
	v_mul_f32_e32 v109, v89, v109
	v_add_f32_e32 v106, v106, v106
	v_fma_f32 v108, v88, v108, v88
	v_fma_f32 v109, v89, v109, v89
	v_mul_f32_e32 v106, 0xbfb8aa3b, v106
	v_mul_f32_e32 v108, 0x3f4c422a, v108
	v_mul_f32_e32 v109, 0x3f4c422a, v109
	v_exp_f32_e32 v106, v106
	v_add_f32_e32 v108, v108, v108
	v_add_f32_e32 v109, v109, v109
	v_mul_f32_e32 v108, 0xbfb8aa3b, v108
	v_mul_f32_e32 v109, 0xbfb8aa3b, v109
	v_exp_f32_e32 v108, v108
	v_exp_f32_e32 v109, v109
	v_add_f32_e32 v106, 1.0, v106
	v_rcp_f32_e32 v106, v106
	v_rcp_f32_e32 v107, v107
	v_add_f32_e32 v108, 1.0, v108
	v_add_f32_e32 v109, 1.0, v109
	v_rcp_f32_e32 v108, v108
	v_rcp_f32_e32 v109, v109
	v_pk_mul_f32 v[110:111], v[86:87], v[106:107]
	s_mov_b64 s[8:9], 0
	v_add_f32_e32 v0, v110, v0
	v_add_f32_e32 v0, v111, v0
	v_pk_mul_f32 v[110:111], v[88:89], v[108:109]
	s_nop 0
	v_add_f32_e32 v0, v110, v0
	v_add_f32_e32 v0, v111, v0
	v_and_b32_e32 v111, 64, v224
	v_xor_b32_e32 v110, 16, v224
	v_add_u32_e32 v111, 64, v111
	v_cmp_lt_i32_e32 vcc, v110, v111
	s_nop 1
	v_cndmask_b32_e32 v110, v224, v110, vcc
	v_lshlrev_b32_e32 v137, 2, v110
	v_mov_b32_e32 v250, v0
	v_mov_b32_e32 v110, v0
	s_nop 1
	v_permlane16_swap_b32_e32 v110, v250
	s_waitcnt lgkmcnt(0)
	v_add_f32_e32 v0, v110, v250
	v_xor_b32_e32 v110, 32, v224
	v_cmp_lt_i32_e32 vcc, v110, v111
	s_nop 1
	v_cndmask_b32_e32 v110, v224, v110, vcc
	v_lshlrev_b32_e32 v138, 2, v110
	v_mov_b32_e32 v250, v0
	v_mov_b32_e32 v110, v0
	s_nop 1
	v_permlane32_swap_b32_e32 v110, v250
	s_waitcnt lgkmcnt(0)
	v_add_f32_e32 v0, v110, v250
	v_mul_f32_e32 v0, 0x3c800000, v0
	v_fma_f32 v140, v99, v113, -v0
	v_fma_f32 v139, v98, v112, -v0
	v_mul_f32_e32 v112, v140, v140
	v_fmac_f32_e32 v112, v139, v139
	v_fma_f32 v114, v100, v114, -v0
	v_fmac_f32_e32 v112, v114, v114
	v_fma_f32 v115, v101, v115, -v0
	v_fmac_f32_e32 v112, v115, v115
	v_fma_f32 v116, v94, v116, -v0
	v_fmac_f32_e32 v112, v116, v116
	v_fma_f32 v117, v95, v117, -v0
	v_fmac_f32_e32 v112, v117, v117
	v_fma_f32 v141, v96, v135, -v0
	v_fmac_f32_e32 v112, v141, v141
	v_fma_f32 v136, v97, v136, -v0
	v_pk_fma_f32 v[110:111], v[90:91], v[102:103], v[0:1] op_sel_hi:[1,1,0] neg_lo:[0,0,1] neg_hi:[0,0,1]
	v_fmac_f32_e32 v112, v136, v136
	v_pk_mul_f32 v[102:103], v[110:111], v[110:111]
	v_pk_fma_f32 v[106:107], v[86:87], v[106:107], v[0:1] op_sel_hi:[1,1,0] neg_lo:[0,0,1] neg_hi:[0,0,1]
	v_add_f32_e32 v102, v102, v112
	v_pk_fma_f32 v[112:113], v[92:93], v[104:105], v[0:1] op_sel_hi:[1,1,0] neg_lo:[0,0,1] neg_hi:[0,0,1]
	v_add_f32_e32 v135, v103, v102
	v_pk_mul_f32 v[102:103], v[112:113], v[112:113]
	v_pk_fma_f32 v[108:109], v[88:89], v[108:109], v[0:1] op_sel_hi:[1,1,0] neg_lo:[0,0,1] neg_hi:[0,0,1]
	v_add_f32_e32 v102, v102, v135
	v_add_f32_e32 v104, v103, v102
	v_pk_mul_f32 v[102:103], v[106:107], v[106:107]
	v_ashrrev_i32_e32 v135, 31, v134
	v_add_f32_e32 v102, v102, v104
	v_add_f32_e32 v104, v103, v102
	v_pk_mul_f32 v[102:103], v[108:109], v[108:109]
	s_nop 0
	v_add_f32_e32 v0, v102, v104
	v_add_f32_e32 v0, v103, v0
	v_mov_b32_e32 v250, v0
	v_mov_b32_e32 v102, v0
	s_nop 1
	v_permlane16_swap_b32_e32 v102, v250
	s_waitcnt lgkmcnt(0)
	v_add_f32_e32 v0, v102, v250
	v_mov_b32_e32 v250, v0
	v_mov_b32_e32 v102, v0
	s_nop 1
	v_permlane32_swap_b32_e32 v102, v250
	s_waitcnt lgkmcnt(0)
	v_add_f32_e32 v0, v102, v250
	v_fmamk_f32 v0, v0, 0x3c800000, v222
	v_mul_f32_e32 v102, 0x4b800000, v0
	v_cmp_gt_f32_e32 vcc, s14, v0
	s_nop 1
	v_cndmask_b32_e32 v0, v0, v102, vcc
	v_rsq_f32_e32 v0, v0
	s_nop 0
	v_mul_f32_e32 v102, 0x45800000, v0
	v_cndmask_b32_e32 v0, v0, v102, vcc
	v_lshlrev_b64 v[102:103], 9, v[134:135]
	v_mul_f32_e32 v104, v139, v0
	v_mul_f32_e32 v105, v140, v0
	v_mul_f32_e32 v135, v114, v0
	v_mul_f32_e32 v137, v115, v0
	v_mul_f32_e32 v116, v116, v0
	v_mul_f32_e32 v117, v117, v0
	v_mul_f32_e32 v138, v141, v0
	v_mul_f32_e32 v136, v136, v0
	v_lshl_add_u64 v[114:115], v[196:197], 0, v[102:103]
	v_cvt_pk_bf16_f32 v102, v104, v105
	v_cvt_pk_bf16_f32 v103, v135, v137
	v_cvt_pk_bf16_f32 v104, v116, v117
	v_cvt_pk_bf16_f32 v105, v138, v136
	global_store_dwordx4 v[114:115], v[102:105], off
	v_mul_f32_e32 v106, v106, v0
	v_mul_f32_e32 v107, v107, v0
	v_mul_f32_e32 v102, v110, v0
	v_mul_f32_e32 v103, v111, v0
	v_mul_f32_e32 v104, v112, v0
	v_mul_f32_e32 v105, v113, v0
	v_mul_f32_e32 v108, v108, v0
	v_mul_f32_e32 v0, v109, v0
	v_cvt_pk_bf16_f32 v102, v102, v103
	v_cvt_pk_bf16_f32 v103, v104, v105
	v_cvt_pk_bf16_f32 v104, v106, v107
	v_cvt_pk_bf16_f32 v105, v108, v0
	global_store_dwordx4 v[114:115], v[102:105], off offset:64

.LBB0_407:
	v_add_u32_e32 v118, s29, v179
	s_mov_b64 s[44:45], -1
	s_mov_b64 s[0:1], 0
	s_cmp_lt_i32 s13, 1
	s_mov_b64 s[8:9], 0
	s_cbranch_scc1 .LBB0_411
	s_cmp_eq_u32 s13, 1
	s_mov_b64 s[8:9], -1
	s_cbranch_scc0 .LBB0_410
	v_mul_f32_e32 v0, 0x3d372713, v82
	v_mul_f32_e32 v0, v82, v0
	v_fma_f32 v0, v82, v0, v82
	v_mul_f32_e32 v0, 0x3f4c422a, v0
	v_add_f32_e32 v0, v0, v0
	v_mul_f32_e32 v0, 0xbfb8aa3b, v0
	v_exp_f32_e32 v0, v0
	v_mul_f32_e32 v86, 0x3d372713, v83
	v_mul_f32_e32 v86, v83, v86
	v_fma_f32 v86, v83, v86, v83
	v_add_f32_e32 v0, 1.0, v0
	v_rcp_f32_e32 v96, v0
	v_mul_f32_e32 v0, 0x3f4c422a, v86
	v_mul_f32_e32 v86, 0x3d372713, v84
	v_mul_f32_e32 v86, v84, v86
	v_mul_f32_e32 v87, 0x3d372713, v85
	v_fma_f32 v86, v84, v86, v84
	v_mul_f32_e32 v87, v85, v87
	v_add_f32_e32 v0, v0, v0
	v_mul_f32_e32 v86, 0x3f4c422a, v86
	v_fma_f32 v87, v85, v87, v85
	v_mul_f32_e32 v0, 0xbfb8aa3b, v0
	v_add_f32_e32 v86, v86, v86
	v_mul_f32_e32 v87, 0x3f4c422a, v87
	v_exp_f32_e32 v0, v0
	v_mul_f32_e32 v86, 0xbfb8aa3b, v86
	v_add_f32_e32 v87, v87, v87
	v_exp_f32_e32 v86, v86
	v_mul_f32_e32 v87, 0xbfb8aa3b, v87
	v_exp_f32_e32 v87, v87
	v_add_f32_e32 v0, 1.0, v0
	v_rcp_f32_e32 v97, v0
	v_add_f32_e32 v0, 1.0, v86
	v_rcp_f32_e32 v98, v0
	v_add_f32_e32 v0, 1.0, v87
	v_rcp_f32_e32 v99, v0
	v_mul_f32_e32 v0, 0x3d372713, v78
	v_mul_f32_e32 v0, v78, v0
	v_mul_f32_e32 v86, 0x3d372713, v79
	v_fma_f32 v0, v78, v0, v78
	v_mul_f32_e32 v86, v79, v86
	v_mul_f32_e32 v87, 0x3d372713, v80
	v_mul_f32_e32 v0, 0x3f4c422a, v0
	v_fma_f32 v86, v79, v86, v79
	v_mul_f32_e32 v87, v80, v87
	v_add_f32_e32 v0, v0, v0
	v_mul_f32_e32 v86, 0x3f4c422a, v86
	v_fma_f32 v87, v80, v87, v80
	v_mul_f32_e32 v0, 0xbfb8aa3b, v0
	v_add_f32_e32 v86, v86, v86
	v_mul_f32_e32 v87, 0x3f4c422a, v87
	v_exp_f32_e32 v0, v0
	v_mul_f32_e32 v86, 0xbfb8aa3b, v86
	v_add_f32_e32 v87, v87, v87
	v_exp_f32_e32 v86, v86
	v_mul_f32_e32 v87, 0xbfb8aa3b, v87
	v_exp_f32_e32 v87, v87
	v_add_f32_e32 v0, 1.0, v0
	v_rcp_f32_e32 v100, v0
	v_add_f32_e32 v0, 1.0, v86
	v_rcp_f32_e32 v101, v0
	v_add_f32_e32 v0, 1.0, v87
	v_rcp_f32_e32 v119, v0
	v_mul_f32_e32 v0, 0x3d372713, v81
	v_mul_f32_e32 v0, v81, v0
	v_fma_f32 v0, v81, v0, v81
	v_mul_f32_e32 v0, 0x3f4c422a, v0
	v_add_f32_e32 v0, v0, v0
	v_mul_f32_e32 v0, 0xbfb8aa3b, v0
	v_exp_f32_e32 v0, v0
	v_mul_f32_e32 v86, 0x3d372713, v75
	v_mul_f32_e32 v86, v75, v86
	v_fma_f32 v86, v75, v86, v75
	v_add_f32_e32 v0, 1.0, v0
	v_rcp_f32_e32 v120, v0
	v_mul_f32_e32 v0, 0x3d372713, v74
	v_mul_f32_e32 v0, v74, v0
	v_fma_f32 v0, v74, v0, v74
	v_mul_f32_e32 v0, 0x3f4c422a, v0
	v_add_f32_e32 v0, v0, v0
	v_mul_f32_e32 v86, 0x3f4c422a, v86
	v_mul_f32_e32 v0, 0xbfb8aa3b, v0
	v_add_f32_e32 v86, v86, v86
	v_exp_f32_e32 v0, v0
	v_mul_f32_e32 v86, 0xbfb8aa3b, v86
	v_exp_f32_e32 v87, v86
	v_fma_f32 v92, v82, v96, 0
	v_add_f32_e32 v0, 1.0, v0
	v_rcp_f32_e32 v86, v0
	v_add_f32_e32 v0, 1.0, v87
	v_mul_f32_e32 v87, 0x3d372713, v76
	v_mul_f32_e32 v87, v76, v87
	v_fma_f32 v87, v76, v87, v76
	v_mul_f32_e32 v87, 0x3f4c422a, v87
	v_add_f32_e32 v87, v87, v87
	v_mul_f32_e32 v87, 0xbfb8aa3b, v87
	v_exp_f32_e32 v88, v87
	v_mul_f32_e32 v87, 0x3d372713, v77
	v_mul_f32_e32 v87, v77, v87
	v_fma_f32 v87, v77, v87, v77
	v_mul_f32_e32 v87, 0x3f4c422a, v87
	v_fmac_f32_e32 v92, v83, v97
	v_add_f32_e32 v87, v87, v87
	v_fmac_f32_e32 v92, v84, v98
	v_mul_f32_e32 v87, 0xbfb8aa3b, v87
	v_fmac_f32_e32 v92, v85, v99
	v_exp_f32_e32 v89, v87
	v_rcp_f32_e32 v87, v0
	v_fmac_f32_e32 v92, v78, v100
	v_fmac_f32_e32 v92, v79, v101
	v_fmac_f32_e32 v92, v80, v119
	v_add_f32_e32 v0, 1.0, v88
	v_fmac_f32_e32 v92, v81, v120
	v_rcp_f32_e32 v88, v0
	v_add_f32_e32 v0, 1.0, v89
	v_pk_mul_f32 v[90:91], v[74:75], v[86:87]
	v_rcp_f32_e32 v89, v0
	v_add_f32_e32 v0, v92, v90
	v_mul_f32_e32 v92, 0x3d372713, v71
	v_mul_f32_e32 v92, v71, v92
	v_fma_f32 v92, v71, v92, v71
	v_mul_f32_e32 v92, 0x3f4c422a, v92
	v_add_f32_e32 v92, v92, v92
	v_mul_f32_e32 v92, 0xbfb8aa3b, v92
	v_exp_f32_e32 v92, v92
	v_add_f32_e32 v0, v91, v0
	v_pk_mul_f32 v[90:91], v[76:77], v[88:89]
	v_mul_f32_e32 v93, 0x3d372713, v73
	v_add_f32_e32 v0, v90, v0
	v_mul_f32_e32 v90, 0x3d372713, v70
	v_mul_f32_e32 v90, v70, v90
	v_fma_f32 v90, v70, v90, v70
	v_add_f32_e32 v0, v91, v0
	v_add_f32_e32 v91, 1.0, v92
	v_mul_f32_e32 v92, 0x3d372713, v72
	v_mul_f32_e32 v90, 0x3f4c422a, v90
	v_mul_f32_e32 v92, v72, v92
	v_mul_f32_e32 v93, v73, v93
	v_add_f32_e32 v90, v90, v90
	v_fma_f32 v92, v72, v92, v72
	v_fma_f32 v93, v73, v93, v73
	v_mul_f32_e32 v90, 0xbfb8aa3b, v90
	v_mul_f32_e32 v92, 0x3f4c422a, v92
	v_mul_f32_e32 v93, 0x3f4c422a, v93
	v_exp_f32_e32 v90, v90
	v_add_f32_e32 v92, v92, v92
	v_add_f32_e32 v93, v93, v93
	v_mul_f32_e32 v92, 0xbfb8aa3b, v92
	v_mul_f32_e32 v93, 0xbfb8aa3b, v93
	v_exp_f32_e32 v92, v92
	v_exp_f32_e32 v93, v93
	v_add_f32_e32 v90, 1.0, v90
	v_rcp_f32_e32 v90, v90
	v_rcp_f32_e32 v91, v91
	v_add_f32_e32 v92, 1.0, v92
	v_add_f32_e32 v93, 1.0, v93
	v_rcp_f32_e32 v92, v92
	v_rcp_f32_e32 v93, v93
	v_pk_mul_f32 v[94:95], v[70:71], v[90:91]
	s_mov_b64 s[8:9], 0
	v_add_f32_e32 v0, v94, v0
	v_add_f32_e32 v0, v95, v0
	v_pk_mul_f32 v[94:95], v[72:73], v[92:93]
	s_nop 0
	v_add_f32_e32 v0, v94, v0
	v_add_f32_e32 v0, v95, v0
	v_and_b32_e32 v95, 64, v224
	v_xor_b32_e32 v94, 16, v224
	v_add_u32_e32 v95, 64, v95
	v_cmp_lt_i32_e32 vcc, v94, v95
	s_nop 1
	v_cndmask_b32_e32 v94, v224, v94, vcc
	v_lshlrev_b32_e32 v121, 2, v94
	v_mov_b32_e32 v250, v0
	v_mov_b32_e32 v94, v0
	s_nop 1
	v_permlane16_swap_b32_e32 v94, v250
	s_waitcnt lgkmcnt(0)
	v_add_f32_e32 v0, v94, v250
	v_xor_b32_e32 v94, 32, v224
	v_cmp_lt_i32_e32 vcc, v94, v95
	s_nop 1
	v_cndmask_b32_e32 v94, v224, v94, vcc
	v_lshlrev_b32_e32 v122, 2, v94
	v_mov_b32_e32 v250, v0
	v_mov_b32_e32 v94, v0
	s_nop 1
	v_permlane32_swap_b32_e32 v94, v250
	s_waitcnt lgkmcnt(0)
	v_add_f32_e32 v0, v94, v250
	v_mul_f32_e32 v0, 0x3c800000, v0
	v_fma_f32 v124, v83, v97, -v0
	v_fma_f32 v123, v82, v96, -v0
	v_mul_f32_e32 v96, v124, v124
	v_fmac_f32_e32 v96, v123, v123
	v_fma_f32 v98, v84, v98, -v0
	v_fmac_f32_e32 v96, v98, v98
	v_fma_f32 v99, v85, v99, -v0
	v_fmac_f32_e32 v96, v99, v99
	v_fma_f32 v100, v78, v100, -v0
	v_fmac_f32_e32 v96, v100, v100
	v_fma_f32 v101, v79, v101, -v0
	v_fmac_f32_e32 v96, v101, v101
	v_fma_f32 v125, v80, v119, -v0
	v_fmac_f32_e32 v96, v125, v125
	v_fma_f32 v120, v81, v120, -v0
	v_pk_fma_f32 v[94:95], v[74:75], v[86:87], v[0:1] op_sel_hi:[1,1,0] neg_lo:[0,0,1] neg_hi:[0,0,1]
	v_fmac_f32_e32 v96, v120, v120
	v_pk_mul_f32 v[86:87], v[94:95], v[94:95]
	v_pk_fma_f32 v[90:91], v[70:71], v[90:91], v[0:1] op_sel_hi:[1,1,0] neg_lo:[0,0,1] neg_hi:[0,0,1]
	v_add_f32_e32 v86, v86, v96
	v_pk_fma_f32 v[96:97], v[76:77], v[88:89], v[0:1] op_sel_hi:[1,1,0] neg_lo:[0,0,1] neg_hi:[0,0,1]
	v_add_f32_e32 v119, v87, v86
	v_pk_mul_f32 v[86:87], v[96:97], v[96:97]
	v_pk_fma_f32 v[92:93], v[72:73], v[92:93], v[0:1] op_sel_hi:[1,1,0] neg_lo:[0,0,1] neg_hi:[0,0,1]
	v_add_f32_e32 v86, v86, v119
	v_add_f32_e32 v88, v87, v86
	v_pk_mul_f32 v[86:87], v[90:91], v[90:91]
	v_ashrrev_i32_e32 v119, 31, v118
	v_add_f32_e32 v86, v86, v88
	v_add_f32_e32 v88, v87, v86
	v_pk_mul_f32 v[86:87], v[92:93], v[92:93]
	s_nop 0
	v_add_f32_e32 v0, v86, v88
	v_add_f32_e32 v0, v87, v0
	v_mov_b32_e32 v250, v0
	v_mov_b32_e32 v86, v0
	s_nop 1
	v_permlane16_swap_b32_e32 v86, v250
	s_waitcnt lgkmcnt(0)
	v_add_f32_e32 v0, v86, v250
	v_mov_b32_e32 v250, v0
	v_mov_b32_e32 v86, v0
	s_nop 1
	v_permlane32_swap_b32_e32 v86, v250
	s_waitcnt lgkmcnt(0)
	v_add_f32_e32 v0, v86, v250
	v_fmamk_f32 v0, v0, 0x3c800000, v222
	v_mul_f32_e32 v86, 0x4b800000, v0
	v_cmp_gt_f32_e32 vcc, s14, v0
	s_nop 1
	v_cndmask_b32_e32 v0, v0, v86, vcc
	v_rsq_f32_e32 v0, v0
	s_nop 0
	v_mul_f32_e32 v86, 0x45800000, v0
	v_cndmask_b32_e32 v0, v0, v86, vcc
	v_lshlrev_b64 v[86:87], 9, v[118:119]
	v_mul_f32_e32 v88, v123, v0
	v_mul_f32_e32 v89, v124, v0
	v_mul_f32_e32 v119, v98, v0
	v_mul_f32_e32 v121, v99, v0
	v_mul_f32_e32 v100, v100, v0
	v_mul_f32_e32 v101, v101, v0
	v_mul_f32_e32 v122, v125, v0
	v_mul_f32_e32 v120, v120, v0
	v_lshl_add_u64 v[98:99], v[196:197], 0, v[86:87]
	v_cvt_pk_bf16_f32 v86, v88, v89
	v_cvt_pk_bf16_f32 v87, v119, v121
	v_cvt_pk_bf16_f32 v88, v100, v101
	v_cvt_pk_bf16_f32 v89, v122, v120
	global_store_dwordx4 v[98:99], v[86:89], off
	v_mul_f32_e32 v90, v90, v0
	v_mul_f32_e32 v91, v91, v0
	v_mul_f32_e32 v86, v94, v0
	v_mul_f32_e32 v87, v95, v0
	v_mul_f32_e32 v88, v96, v0
	v_mul_f32_e32 v89, v97, v0
	v_mul_f32_e32 v92, v92, v0
	v_mul_f32_e32 v0, v93, v0
	v_cvt_pk_bf16_f32 v86, v86, v87
	v_cvt_pk_bf16_f32 v87, v88, v89
	v_cvt_pk_bf16_f32 v88, v90, v91
	v_cvt_pk_bf16_f32 v89, v92, v0
	global_store_dwordx4 v[98:99], v[86:89], off offset:64

.LBB0_453:
	v_add_u32_e32 v102, s29, v181
	s_mov_b64 s[44:45], -1
	s_mov_b64 s[0:1], 0
	s_cmp_lt_i32 s13, 1
	s_mov_b64 s[8:9], 0
	s_cbranch_scc1 .LBB0_457
	s_cmp_eq_u32 s13, 1
	s_mov_b64 s[8:9], -1
	s_cbranch_scc0 .LBB0_456
	v_mul_f32_e32 v0, 0x3d372713, v66
	v_mul_f32_e32 v0, v66, v0
	v_fma_f32 v0, v66, v0, v66
	v_mul_f32_e32 v0, 0x3f4c422a, v0
	v_add_f32_e32 v0, v0, v0
	v_mul_f32_e32 v0, 0xbfb8aa3b, v0
	v_exp_f32_e32 v0, v0
	v_mul_f32_e32 v70, 0x3d372713, v67
	v_mul_f32_e32 v70, v67, v70
	v_fma_f32 v70, v67, v70, v67
	v_add_f32_e32 v0, 1.0, v0
	v_rcp_f32_e32 v80, v0
	v_mul_f32_e32 v0, 0x3f4c422a, v70
	v_mul_f32_e32 v70, 0x3d372713, v68
	v_mul_f32_e32 v70, v68, v70
	v_mul_f32_e32 v71, 0x3d372713, v69
	v_fma_f32 v70, v68, v70, v68
	v_mul_f32_e32 v71, v69, v71
	v_add_f32_e32 v0, v0, v0
	v_mul_f32_e32 v70, 0x3f4c422a, v70
	v_fma_f32 v71, v69, v71, v69
	v_mul_f32_e32 v0, 0xbfb8aa3b, v0
	v_add_f32_e32 v70, v70, v70
	v_mul_f32_e32 v71, 0x3f4c422a, v71
	v_exp_f32_e32 v0, v0
	v_mul_f32_e32 v70, 0xbfb8aa3b, v70
	v_add_f32_e32 v71, v71, v71
	v_exp_f32_e32 v70, v70
	v_mul_f32_e32 v71, 0xbfb8aa3b, v71
	v_exp_f32_e32 v71, v71
	v_add_f32_e32 v0, 1.0, v0
	v_rcp_f32_e32 v81, v0
	v_add_f32_e32 v0, 1.0, v70
	v_rcp_f32_e32 v82, v0
	v_add_f32_e32 v0, 1.0, v71
	v_rcp_f32_e32 v83, v0
	v_mul_f32_e32 v0, 0x3d372713, v62
	v_mul_f32_e32 v0, v62, v0
	v_mul_f32_e32 v70, 0x3d372713, v63
	v_fma_f32 v0, v62, v0, v62
	v_mul_f32_e32 v70, v63, v70
	v_mul_f32_e32 v71, 0x3d372713, v64
	v_mul_f32_e32 v0, 0x3f4c422a, v0
	v_fma_f32 v70, v63, v70, v63
	v_mul_f32_e32 v71, v64, v71
	v_add_f32_e32 v0, v0, v0
	v_mul_f32_e32 v70, 0x3f4c422a, v70
	v_fma_f32 v71, v64, v71, v64
	v_mul_f32_e32 v0, 0xbfb8aa3b, v0
	v_add_f32_e32 v70, v70, v70
	v_mul_f32_e32 v71, 0x3f4c422a, v71
	v_exp_f32_e32 v0, v0
	v_mul_f32_e32 v70, 0xbfb8aa3b, v70
	v_add_f32_e32 v71, v71, v71
	v_exp_f32_e32 v70, v70
	v_mul_f32_e32 v71, 0xbfb8aa3b, v71
	v_exp_f32_e32 v71, v71
	v_add_f32_e32 v0, 1.0, v0
	v_rcp_f32_e32 v84, v0
	v_add_f32_e32 v0, 1.0, v70
	v_rcp_f32_e32 v85, v0
	v_add_f32_e32 v0, 1.0, v71
	v_rcp_f32_e32 v103, v0
	v_mul_f32_e32 v0, 0x3d372713, v65
	v_mul_f32_e32 v0, v65, v0
	v_fma_f32 v0, v65, v0, v65
	v_mul_f32_e32 v0, 0x3f4c422a, v0
	v_add_f32_e32 v0, v0, v0
	v_mul_f32_e32 v0, 0xbfb8aa3b, v0
	v_exp_f32_e32 v0, v0
	v_mul_f32_e32 v70, 0x3d372713, v59
	v_mul_f32_e32 v70, v59, v70
	v_fma_f32 v70, v59, v70, v59
	v_add_f32_e32 v0, 1.0, v0
	v_rcp_f32_e32 v104, v0
	v_mul_f32_e32 v0, 0x3d372713, v58
	v_mul_f32_e32 v0, v58, v0
	v_fma_f32 v0, v58, v0, v58
	v_mul_f32_e32 v0, 0x3f4c422a, v0
	v_add_f32_e32 v0, v0, v0
	v_mul_f32_e32 v70, 0x3f4c422a, v70
	v_mul_f32_e32 v0, 0xbfb8aa3b, v0
	v_add_f32_e32 v70, v70, v70
	v_exp_f32_e32 v0, v0
	v_mul_f32_e32 v70, 0xbfb8aa3b, v70
	v_exp_f32_e32 v71, v70
	v_fma_f32 v76, v66, v80, 0
	v_add_f32_e32 v0, 1.0, v0
	v_rcp_f32_e32 v70, v0
	v_add_f32_e32 v0, 1.0, v71
	v_mul_f32_e32 v71, 0x3d372713, v60
	v_mul_f32_e32 v71, v60, v71
	v_fma_f32 v71, v60, v71, v60
	v_mul_f32_e32 v71, 0x3f4c422a, v71
	v_add_f32_e32 v71, v71, v71
	v_mul_f32_e32 v71, 0xbfb8aa3b, v71
	v_exp_f32_e32 v72, v71
	v_mul_f32_e32 v71, 0x3d372713, v61
	v_mul_f32_e32 v71, v61, v71
	v_fma_f32 v71, v61, v71, v61
	v_mul_f32_e32 v71, 0x3f4c422a, v71
	v_fmac_f32_e32 v76, v67, v81
	v_add_f32_e32 v71, v71, v71
	v_fmac_f32_e32 v76, v68, v82
	v_mul_f32_e32 v71, 0xbfb8aa3b, v71
	v_fmac_f32_e32 v76, v69, v83
	v_exp_f32_e32 v73, v71
	v_rcp_f32_e32 v71, v0
	v_fmac_f32_e32 v76, v62, v84
	v_fmac_f32_e32 v76, v63, v85
	v_fmac_f32_e32 v76, v64, v103
	v_add_f32_e32 v0, 1.0, v72
	v_fmac_f32_e32 v76, v65, v104
	v_rcp_f32_e32 v72, v0
	v_add_f32_e32 v0, 1.0, v73
	v_pk_mul_f32 v[74:75], v[58:59], v[70:71]
	v_rcp_f32_e32 v73, v0
	v_add_f32_e32 v0, v76, v74
	v_mul_f32_e32 v76, 0x3d372713, v55
	v_mul_f32_e32 v76, v55, v76
	v_fma_f32 v76, v55, v76, v55
	v_mul_f32_e32 v76, 0x3f4c422a, v76
	v_add_f32_e32 v76, v76, v76
	v_mul_f32_e32 v76, 0xbfb8aa3b, v76
	v_exp_f32_e32 v76, v76
	v_add_f32_e32 v0, v75, v0
	v_pk_mul_f32 v[74:75], v[60:61], v[72:73]
	v_mul_f32_e32 v77, 0x3d372713, v57
	v_add_f32_e32 v0, v74, v0
	v_mul_f32_e32 v74, 0x3d372713, v54
	v_mul_f32_e32 v74, v54, v74
	v_fma_f32 v74, v54, v74, v54
	v_add_f32_e32 v0, v75, v0
	v_add_f32_e32 v75, 1.0, v76
	v_mul_f32_e32 v76, 0x3d372713, v56
	v_mul_f32_e32 v74, 0x3f4c422a, v74
	v_mul_f32_e32 v76, v56, v76
	v_mul_f32_e32 v77, v57, v77
	v_add_f32_e32 v74, v74, v74
	v_fma_f32 v76, v56, v76, v56
	v_fma_f32 v77, v57, v77, v57
	v_mul_f32_e32 v74, 0xbfb8aa3b, v74
	v_mul_f32_e32 v76, 0x3f4c422a, v76
	v_mul_f32_e32 v77, 0x3f4c422a, v77
	v_exp_f32_e32 v74, v74
	v_add_f32_e32 v76, v76, v76
	v_add_f32_e32 v77, v77, v77
	v_mul_f32_e32 v76, 0xbfb8aa3b, v76
	v_mul_f32_e32 v77, 0xbfb8aa3b, v77
	v_exp_f32_e32 v76, v76
	v_exp_f32_e32 v77, v77
	v_add_f32_e32 v74, 1.0, v74
	v_rcp_f32_e32 v74, v74
	v_rcp_f32_e32 v75, v75
	v_add_f32_e32 v76, 1.0, v76
	v_add_f32_e32 v77, 1.0, v77
	v_rcp_f32_e32 v76, v76
	v_rcp_f32_e32 v77, v77
	v_pk_mul_f32 v[78:79], v[54:55], v[74:75]
	s_mov_b64 s[8:9], 0
	v_add_f32_e32 v0, v78, v0
	v_add_f32_e32 v0, v79, v0
	v_pk_mul_f32 v[78:79], v[56:57], v[76:77]
	s_nop 0
	v_add_f32_e32 v0, v78, v0
	v_add_f32_e32 v0, v79, v0
	v_and_b32_e32 v79, 64, v224
	v_xor_b32_e32 v78, 16, v224
	v_add_u32_e32 v79, 64, v79
	v_cmp_lt_i32_e32 vcc, v78, v79
	s_nop 1
	v_cndmask_b32_e32 v78, v224, v78, vcc
	v_lshlrev_b32_e32 v105, 2, v78
	v_mov_b32_e32 v250, v0
	v_mov_b32_e32 v78, v0
	s_nop 1
	v_permlane16_swap_b32_e32 v78, v250
	s_waitcnt lgkmcnt(0)
	v_add_f32_e32 v0, v78, v250
	v_xor_b32_e32 v78, 32, v224
	v_cmp_lt_i32_e32 vcc, v78, v79
	s_nop 1
	v_cndmask_b32_e32 v78, v224, v78, vcc
	v_lshlrev_b32_e32 v106, 2, v78
	v_mov_b32_e32 v250, v0
	v_mov_b32_e32 v78, v0
	s_nop 1
	v_permlane32_swap_b32_e32 v78, v250
	s_waitcnt lgkmcnt(0)
	v_add_f32_e32 v0, v78, v250
	v_mul_f32_e32 v0, 0x3c800000, v0
	v_fma_f32 v108, v67, v81, -v0
	v_fma_f32 v107, v66, v80, -v0
	v_mul_f32_e32 v80, v108, v108
	v_fmac_f32_e32 v80, v107, v107
	v_fma_f32 v82, v68, v82, -v0
	v_fmac_f32_e32 v80, v82, v82
	v_fma_f32 v83, v69, v83, -v0
	v_fmac_f32_e32 v80, v83, v83
	v_fma_f32 v84, v62, v84, -v0
	v_fmac_f32_e32 v80, v84, v84
	v_fma_f32 v85, v63, v85, -v0
	v_fmac_f32_e32 v80, v85, v85
	v_fma_f32 v109, v64, v103, -v0
	v_fmac_f32_e32 v80, v109, v109
	v_fma_f32 v104, v65, v104, -v0
	v_pk_fma_f32 v[78:79], v[58:59], v[70:71], v[0:1] op_sel_hi:[1,1,0] neg_lo:[0,0,1] neg_hi:[0,0,1]
	v_fmac_f32_e32 v80, v104, v104
	v_pk_mul_f32 v[70:71], v[78:79], v[78:79]
	v_pk_fma_f32 v[74:75], v[54:55], v[74:75], v[0:1] op_sel_hi:[1,1,0] neg_lo:[0,0,1] neg_hi:[0,0,1]
	v_add_f32_e32 v70, v70, v80
	v_pk_fma_f32 v[80:81], v[60:61], v[72:73], v[0:1] op_sel_hi:[1,1,0] neg_lo:[0,0,1] neg_hi:[0,0,1]
	v_add_f32_e32 v103, v71, v70
	v_pk_mul_f32 v[70:71], v[80:81], v[80:81]
	v_pk_fma_f32 v[76:77], v[56:57], v[76:77], v[0:1] op_sel_hi:[1,1,0] neg_lo:[0,0,1] neg_hi:[0,0,1]
	v_add_f32_e32 v70, v70, v103
	v_add_f32_e32 v72, v71, v70
	v_pk_mul_f32 v[70:71], v[74:75], v[74:75]
	v_ashrrev_i32_e32 v103, 31, v102
	v_add_f32_e32 v70, v70, v72
	v_add_f32_e32 v72, v71, v70
	v_pk_mul_f32 v[70:71], v[76:77], v[76:77]
	s_nop 0
	v_add_f32_e32 v0, v70, v72
	v_add_f32_e32 v0, v71, v0
	v_mov_b32_e32 v250, v0
	v_mov_b32_e32 v70, v0
	s_nop 1
	v_permlane16_swap_b32_e32 v70, v250
	s_waitcnt lgkmcnt(0)
	v_add_f32_e32 v0, v70, v250
	v_mov_b32_e32 v250, v0
	v_mov_b32_e32 v70, v0
	s_nop 1
	v_permlane32_swap_b32_e32 v70, v250
	s_waitcnt lgkmcnt(0)
	v_add_f32_e32 v0, v70, v250
	v_fmamk_f32 v0, v0, 0x3c800000, v222
	v_mul_f32_e32 v70, 0x4b800000, v0
	v_cmp_gt_f32_e32 vcc, s14, v0
	s_nop 1
	v_cndmask_b32_e32 v0, v0, v70, vcc
	v_rsq_f32_e32 v0, v0
	s_nop 0
	v_mul_f32_e32 v70, 0x45800000, v0
	v_cndmask_b32_e32 v0, v0, v70, vcc
	v_lshlrev_b64 v[70:71], 9, v[102:103]
	v_mul_f32_e32 v72, v107, v0
	v_mul_f32_e32 v73, v108, v0
	v_mul_f32_e32 v103, v82, v0
	v_mul_f32_e32 v105, v83, v0
	v_mul_f32_e32 v84, v84, v0
	v_mul_f32_e32 v85, v85, v0
	v_mul_f32_e32 v106, v109, v0
	v_mul_f32_e32 v104, v104, v0
	v_lshl_add_u64 v[82:83], v[196:197], 0, v[70:71]
	v_cvt_pk_bf16_f32 v70, v72, v73
	v_cvt_pk_bf16_f32 v71, v103, v105
	v_cvt_pk_bf16_f32 v72, v84, v85
	v_cvt_pk_bf16_f32 v73, v106, v104
	global_store_dwordx4 v[82:83], v[70:73], off
	v_mul_f32_e32 v74, v74, v0
	v_mul_f32_e32 v75, v75, v0
	v_mul_f32_e32 v70, v78, v0
	v_mul_f32_e32 v71, v79, v0
	v_mul_f32_e32 v72, v80, v0
	v_mul_f32_e32 v73, v81, v0
	v_mul_f32_e32 v76, v76, v0
	v_mul_f32_e32 v0, v77, v0
	v_cvt_pk_bf16_f32 v70, v70, v71
	v_cvt_pk_bf16_f32 v71, v72, v73
	v_cvt_pk_bf16_f32 v72, v74, v75
	v_cvt_pk_bf16_f32 v73, v76, v0
	global_store_dwordx4 v[82:83], v[70:73], off offset:64

.LBB0_499:
	v_add_u32_e32 v86, s29, v183
	s_mov_b64 s[44:45], -1
	s_mov_b64 s[0:1], 0
	s_cmp_lt_i32 s13, 1
	s_mov_b64 s[8:9], 0
	s_cbranch_scc1 .LBB0_503
	s_cmp_eq_u32 s13, 1
	s_mov_b64 s[8:9], -1
	s_cbranch_scc0 .LBB0_502
	v_mul_f32_e32 v0, 0x3d372713, v50
	v_mul_f32_e32 v0, v50, v0
	v_fma_f32 v0, v50, v0, v50
	v_mul_f32_e32 v0, 0x3f4c422a, v0
	v_add_f32_e32 v0, v0, v0
	v_mul_f32_e32 v0, 0xbfb8aa3b, v0
	v_exp_f32_e32 v0, v0
	v_mul_f32_e32 v54, 0x3d372713, v51
	v_mul_f32_e32 v54, v51, v54
	v_fma_f32 v54, v51, v54, v51
	v_add_f32_e32 v0, 1.0, v0
	v_rcp_f32_e32 v64, v0
	v_mul_f32_e32 v0, 0x3f4c422a, v54
	v_mul_f32_e32 v54, 0x3d372713, v52
	v_mul_f32_e32 v54, v52, v54
	v_mul_f32_e32 v55, 0x3d372713, v53
	v_fma_f32 v54, v52, v54, v52
	v_mul_f32_e32 v55, v53, v55
	v_add_f32_e32 v0, v0, v0
	v_mul_f32_e32 v54, 0x3f4c422a, v54
	v_fma_f32 v55, v53, v55, v53
	v_mul_f32_e32 v0, 0xbfb8aa3b, v0
	v_add_f32_e32 v54, v54, v54
	v_mul_f32_e32 v55, 0x3f4c422a, v55
	v_exp_f32_e32 v0, v0
	v_mul_f32_e32 v54, 0xbfb8aa3b, v54
	v_add_f32_e32 v55, v55, v55
	v_exp_f32_e32 v54, v54
	v_mul_f32_e32 v55, 0xbfb8aa3b, v55
	v_exp_f32_e32 v55, v55
	v_add_f32_e32 v0, 1.0, v0
	v_rcp_f32_e32 v65, v0
	v_add_f32_e32 v0, 1.0, v54
	v_rcp_f32_e32 v66, v0
	v_add_f32_e32 v0, 1.0, v55
	v_rcp_f32_e32 v67, v0
	v_mul_f32_e32 v0, 0x3d372713, v46
	v_mul_f32_e32 v0, v46, v0
	v_mul_f32_e32 v54, 0x3d372713, v47
	v_fma_f32 v0, v46, v0, v46
	v_mul_f32_e32 v54, v47, v54
	v_mul_f32_e32 v55, 0x3d372713, v48
	v_mul_f32_e32 v0, 0x3f4c422a, v0
	v_fma_f32 v54, v47, v54, v47
	v_mul_f32_e32 v55, v48, v55
	v_add_f32_e32 v0, v0, v0
	v_mul_f32_e32 v54, 0x3f4c422a, v54
	v_fma_f32 v55, v48, v55, v48
	v_mul_f32_e32 v0, 0xbfb8aa3b, v0
	v_add_f32_e32 v54, v54, v54
	v_mul_f32_e32 v55, 0x3f4c422a, v55
	v_exp_f32_e32 v0, v0
	v_mul_f32_e32 v54, 0xbfb8aa3b, v54
	v_add_f32_e32 v55, v55, v55
	v_exp_f32_e32 v54, v54
	v_mul_f32_e32 v55, 0xbfb8aa3b, v55
	v_exp_f32_e32 v55, v55
	v_add_f32_e32 v0, 1.0, v0
	v_rcp_f32_e32 v68, v0
	v_add_f32_e32 v0, 1.0, v54
	v_rcp_f32_e32 v69, v0
	v_add_f32_e32 v0, 1.0, v55
	v_rcp_f32_e32 v87, v0
	v_mul_f32_e32 v0, 0x3d372713, v49
	v_mul_f32_e32 v0, v49, v0
	v_fma_f32 v0, v49, v0, v49
	v_mul_f32_e32 v0, 0x3f4c422a, v0
	v_add_f32_e32 v0, v0, v0
	v_mul_f32_e32 v0, 0xbfb8aa3b, v0
	v_exp_f32_e32 v0, v0
	v_mul_f32_e32 v54, 0x3d372713, v43
	v_mul_f32_e32 v54, v43, v54
	v_fma_f32 v54, v43, v54, v43
	v_add_f32_e32 v0, 1.0, v0
	v_rcp_f32_e32 v88, v0
	v_mul_f32_e32 v0, 0x3d372713, v42
	v_mul_f32_e32 v0, v42, v0
	v_fma_f32 v0, v42, v0, v42
	v_mul_f32_e32 v0, 0x3f4c422a, v0
	v_add_f32_e32 v0, v0, v0
	v_mul_f32_e32 v54, 0x3f4c422a, v54
	v_mul_f32_e32 v0, 0xbfb8aa3b, v0
	v_add_f32_e32 v54, v54, v54
	v_exp_f32_e32 v0, v0
	v_mul_f32_e32 v54, 0xbfb8aa3b, v54
	v_exp_f32_e32 v55, v54
	v_fma_f32 v60, v50, v64, 0
	v_add_f32_e32 v0, 1.0, v0
	v_rcp_f32_e32 v54, v0
	v_add_f32_e32 v0, 1.0, v55
	v_mul_f32_e32 v55, 0x3d372713, v44
	v_mul_f32_e32 v55, v44, v55
	v_fma_f32 v55, v44, v55, v44
	v_mul_f32_e32 v55, 0x3f4c422a, v55
	v_add_f32_e32 v55, v55, v55
	v_mul_f32_e32 v55, 0xbfb8aa3b, v55
	v_exp_f32_e32 v56, v55
	v_mul_f32_e32 v55, 0x3d372713, v45
	v_mul_f32_e32 v55, v45, v55
	v_fma_f32 v55, v45, v55, v45
	v_mul_f32_e32 v55, 0x3f4c422a, v55
	v_fmac_f32_e32 v60, v51, v65
	v_add_f32_e32 v55, v55, v55
	v_fmac_f32_e32 v60, v52, v66
	v_mul_f32_e32 v55, 0xbfb8aa3b, v55
	v_fmac_f32_e32 v60, v53, v67
	v_exp_f32_e32 v57, v55
	v_rcp_f32_e32 v55, v0
	v_fmac_f32_e32 v60, v46, v68
	v_fmac_f32_e32 v60, v47, v69
	v_fmac_f32_e32 v60, v48, v87
	v_add_f32_e32 v0, 1.0, v56
	v_fmac_f32_e32 v60, v49, v88
	v_rcp_f32_e32 v56, v0
	v_add_f32_e32 v0, 1.0, v57
	v_pk_mul_f32 v[58:59], v[42:43], v[54:55]
	v_rcp_f32_e32 v57, v0
	v_add_f32_e32 v0, v60, v58
	v_mul_f32_e32 v60, 0x3d372713, v31
	v_mul_f32_e32 v60, v31, v60
	v_fma_f32 v60, v31, v60, v31
	v_mul_f32_e32 v60, 0x3f4c422a, v60
	v_add_f32_e32 v60, v60, v60
	v_mul_f32_e32 v60, 0xbfb8aa3b, v60
	v_exp_f32_e32 v60, v60
	v_add_f32_e32 v0, v59, v0
	v_pk_mul_f32 v[58:59], v[44:45], v[56:57]
	v_mul_f32_e32 v61, 0x3d372713, v33
	v_add_f32_e32 v0, v58, v0
	v_mul_f32_e32 v58, 0x3d372713, v30
	v_mul_f32_e32 v58, v30, v58
	v_fma_f32 v58, v30, v58, v30
	v_add_f32_e32 v0, v59, v0
	v_add_f32_e32 v59, 1.0, v60
	v_mul_f32_e32 v60, 0x3d372713, v32
	v_mul_f32_e32 v58, 0x3f4c422a, v58
	v_mul_f32_e32 v60, v32, v60
	v_mul_f32_e32 v61, v33, v61
	v_add_f32_e32 v58, v58, v58
	v_fma_f32 v60, v32, v60, v32
	v_fma_f32 v61, v33, v61, v33
	v_mul_f32_e32 v58, 0xbfb8aa3b, v58
	v_mul_f32_e32 v60, 0x3f4c422a, v60
	v_mul_f32_e32 v61, 0x3f4c422a, v61
	v_exp_f32_e32 v58, v58
	v_add_f32_e32 v60, v60, v60
	v_add_f32_e32 v61, v61, v61
	v_mul_f32_e32 v60, 0xbfb8aa3b, v60
	v_mul_f32_e32 v61, 0xbfb8aa3b, v61
	v_exp_f32_e32 v60, v60
	v_exp_f32_e32 v61, v61
	v_add_f32_e32 v58, 1.0, v58
	v_rcp_f32_e32 v58, v58
	v_rcp_f32_e32 v59, v59
	v_add_f32_e32 v60, 1.0, v60
	v_add_f32_e32 v61, 1.0, v61
	v_rcp_f32_e32 v60, v60
	v_rcp_f32_e32 v61, v61
	v_pk_mul_f32 v[62:63], v[30:31], v[58:59]
	s_mov_b64 s[8:9], 0
	v_add_f32_e32 v0, v62, v0
	v_add_f32_e32 v0, v63, v0
	v_pk_mul_f32 v[62:63], v[32:33], v[60:61]
	s_nop 0
	v_add_f32_e32 v0, v62, v0
	v_add_f32_e32 v0, v63, v0
	v_and_b32_e32 v63, 64, v224
	v_xor_b32_e32 v62, 16, v224
	v_add_u32_e32 v63, 64, v63
	v_cmp_lt_i32_e32 vcc, v62, v63
	s_nop 1
	v_cndmask_b32_e32 v62, v224, v62, vcc
	v_lshlrev_b32_e32 v89, 2, v62
	v_mov_b32_e32 v250, v0
	v_mov_b32_e32 v62, v0
	s_nop 1
	v_permlane16_swap_b32_e32 v62, v250
	s_waitcnt lgkmcnt(0)
	v_add_f32_e32 v0, v62, v250
	v_xor_b32_e32 v62, 32, v224
	v_cmp_lt_i32_e32 vcc, v62, v63
	s_nop 1
	v_cndmask_b32_e32 v62, v224, v62, vcc
	v_lshlrev_b32_e32 v90, 2, v62
	v_mov_b32_e32 v250, v0
	v_mov_b32_e32 v62, v0
	s_nop 1
	v_permlane32_swap_b32_e32 v62, v250
	s_waitcnt lgkmcnt(0)
	v_add_f32_e32 v0, v62, v250
	v_mul_f32_e32 v0, 0x3c800000, v0
	v_fma_f32 v92, v51, v65, -v0
	v_fma_f32 v91, v50, v64, -v0
	v_mul_f32_e32 v64, v92, v92
	v_fmac_f32_e32 v64, v91, v91
	v_fma_f32 v66, v52, v66, -v0
	v_fmac_f32_e32 v64, v66, v66
	v_fma_f32 v67, v53, v67, -v0
	v_fmac_f32_e32 v64, v67, v67
	v_fma_f32 v68, v46, v68, -v0
	v_fmac_f32_e32 v64, v68, v68
	v_fma_f32 v69, v47, v69, -v0
	v_fmac_f32_e32 v64, v69, v69
	v_fma_f32 v93, v48, v87, -v0
	v_fmac_f32_e32 v64, v93, v93
	v_fma_f32 v88, v49, v88, -v0
	v_pk_fma_f32 v[62:63], v[42:43], v[54:55], v[0:1] op_sel_hi:[1,1,0] neg_lo:[0,0,1] neg_hi:[0,0,1]
	v_fmac_f32_e32 v64, v88, v88
	v_pk_mul_f32 v[54:55], v[62:63], v[62:63]
	v_pk_fma_f32 v[58:59], v[30:31], v[58:59], v[0:1] op_sel_hi:[1,1,0] neg_lo:[0,0,1] neg_hi:[0,0,1]
	v_add_f32_e32 v54, v54, v64
	v_pk_fma_f32 v[64:65], v[44:45], v[56:57], v[0:1] op_sel_hi:[1,1,0] neg_lo:[0,0,1] neg_hi:[0,0,1]
	v_add_f32_e32 v87, v55, v54
	v_pk_mul_f32 v[54:55], v[64:65], v[64:65]
	v_pk_fma_f32 v[60:61], v[32:33], v[60:61], v[0:1] op_sel_hi:[1,1,0] neg_lo:[0,0,1] neg_hi:[0,0,1]
	v_add_f32_e32 v54, v54, v87
	v_add_f32_e32 v56, v55, v54
	v_pk_mul_f32 v[54:55], v[58:59], v[58:59]
	v_ashrrev_i32_e32 v87, 31, v86
	v_add_f32_e32 v54, v54, v56
	v_add_f32_e32 v56, v55, v54
	v_pk_mul_f32 v[54:55], v[60:61], v[60:61]
	s_nop 0
	v_add_f32_e32 v0, v54, v56
	v_add_f32_e32 v0, v55, v0
	v_mov_b32_e32 v250, v0
	v_mov_b32_e32 v54, v0
	s_nop 1
	v_permlane16_swap_b32_e32 v54, v250
	s_waitcnt lgkmcnt(0)
	v_add_f32_e32 v0, v54, v250
	v_mov_b32_e32 v250, v0
	v_mov_b32_e32 v54, v0
	s_nop 1
	v_permlane32_swap_b32_e32 v54, v250
	s_waitcnt lgkmcnt(0)
	v_add_f32_e32 v0, v54, v250
	v_fmamk_f32 v0, v0, 0x3c800000, v222
	v_mul_f32_e32 v54, 0x4b800000, v0
	v_cmp_gt_f32_e32 vcc, s14, v0
	s_nop 1
	v_cndmask_b32_e32 v0, v0, v54, vcc
	v_rsq_f32_e32 v0, v0
	s_nop 0
	v_mul_f32_e32 v54, 0x45800000, v0
	v_cndmask_b32_e32 v0, v0, v54, vcc
	v_lshlrev_b64 v[54:55], 9, v[86:87]
	v_mul_f32_e32 v56, v91, v0
	v_mul_f32_e32 v57, v92, v0
	v_mul_f32_e32 v87, v66, v0
	v_mul_f32_e32 v89, v67, v0
	v_mul_f32_e32 v68, v68, v0
	v_mul_f32_e32 v69, v69, v0
	v_mul_f32_e32 v90, v93, v0
	v_mul_f32_e32 v88, v88, v0
	v_lshl_add_u64 v[66:67], v[196:197], 0, v[54:55]
	v_cvt_pk_bf16_f32 v54, v56, v57
	v_cvt_pk_bf16_f32 v55, v87, v89
	v_cvt_pk_bf16_f32 v56, v68, v69
	v_cvt_pk_bf16_f32 v57, v90, v88
	global_store_dwordx4 v[66:67], v[54:57], off
	v_mul_f32_e32 v58, v58, v0
	v_mul_f32_e32 v59, v59, v0
	v_mul_f32_e32 v54, v62, v0
	v_mul_f32_e32 v55, v63, v0
	v_mul_f32_e32 v56, v64, v0
	v_mul_f32_e32 v57, v65, v0
	v_mul_f32_e32 v60, v60, v0
	v_mul_f32_e32 v0, v61, v0
	v_cvt_pk_bf16_f32 v54, v54, v55
	v_cvt_pk_bf16_f32 v55, v56, v57
	v_cvt_pk_bf16_f32 v56, v58, v59
	v_cvt_pk_bf16_f32 v57, v60, v0
	global_store_dwordx4 v[66:67], v[54:57], off offset:64

.LBB0_564:
	s_and_b64 vcc, exec, s[0:1]
	s_cbranch_vccz .LBB0_593
	v_mul_f32_e32 v0, v19, v19
	v_fmac_f32_e32 v0, v18, v18
	v_fmac_f32_e32 v0, v20, v20
	v_fmac_f32_e32 v0, v21, v21
	v_fmac_f32_e32 v0, v14, v14
	v_fmac_f32_e32 v0, v15, v15
	v_fmac_f32_e32 v0, v16, v16
	v_fmac_f32_e32 v0, v17, v17
	v_pk_mul_f32 v[42:43], v[10:11], v[10:11]
	v_pk_mul_f32 v[32:33], v[12:13], v[12:13]
	v_add_f32_e32 v0, v0, v42
	v_add_f32_e32 v0, v43, v0
	v_add_f32_e32 v0, v32, v0
	v_add_f32_e32 v0, v33, v0
	v_pk_mul_f32 v[42:43], v[6:7], v[6:7]
	v_pk_mul_f32 v[32:33], v[8:9], v[8:9]
	v_add_f32_e32 v0, v42, v0
	v_add_f32_e32 v0, v43, v0
	v_add_f32_e32 v0, v32, v0
	v_and_b32_e32 v32, 64, v224
	v_xor_b32_e32 v31, 16, v224
	v_add_u32_e32 v32, 64, v32
	v_cmp_lt_i32_e32 vcc, v31, v32
	v_add_f32_e32 v0, v33, v0
	s_nop 0
	v_cndmask_b32_e32 v31, v224, v31, vcc
	v_lshlrev_b32_e32 v31, 2, v31
	v_mov_b32_e32 v250, v0
	v_mov_b32_e32 v31, v0
	s_nop 1
	v_permlane16_swap_b32_e32 v31, v250
	s_waitcnt lgkmcnt(0)
	v_add_f32_e32 v31, v31, v250
	v_xor_b32_e32 v0, 32, v224
	v_cmp_lt_i32_e32 vcc, v0, v32
	s_nop 1
	v_cndmask_b32_e32 v0, v224, v0, vcc
	v_lshlrev_b32_e32 v42, 2, v0
	ds_bpermute_b32 v32, v42, v31
	v_cndmask_b32_e64 v0, 0, 1, s[38:39]
	v_cmp_ne_u32_e64 s[0:1], 1, v0
	s_andn2_b64 vcc, exec, s[38:39]
	s_cbranch_vccnz .LBB0_567
	v_lshlrev_b32_e32 v0, 1, v30
	v_and_b32_e32 v0, 0x3f80, v0
	v_lshl_add_u64 v[44:45], v[186:187], 0, v[0:1]
	global_load_dwordx4 v[54:57], v[44:45], off offset:48
	global_load_dwordx4 v[58:61], v[44:45], off offset:32
	global_load_dwordx4 v[62:65], v[44:45], off offset:16
	global_load_dwordx4 v[66:69], v[44:45], off
